# K-loop v4: trailing barrier 2 MFMAs early with priority ladder (M-wave prio 2, tail prio 3)
# speedup vs baseline: 1.0348x; 1.0153x over previous
; #define PG8_STAGE(bufoff, gbase, voff) do { _Pragma("unroll") for (int _i = 0; _i < 2; ++_i) \
;         __builtin_amdgcn_global_load_lds((const unsigned*)((const char*)(gbase) + (voff)[_i]), (PG8_LAS unsigned*)(lds + (bufoff) + ldsw + _i * 8192), 16, 0, 0); } while (0)
; #define PG8_LDA(dst, b, h) do { _Pragma("unroll") for (int m = 0; m < 4; ++m) _Pragma("unroll") for (int k = 0; k < 2; ++k) dst[m][k] = *(const PG8_LAS bf16x8*)(lds + PG8_SA(b, h) + aoff + m * 2048 + k * 1024); } while (0)
; #define PG8_MMA(ai, bj, At, Bt) do { __builtin_amdgcn_s_setprio(1); _Pragma("unroll") for (int m = 0; m < 4; ++m) _Pragma("unroll") for (int n = 0; n < 2; ++n) _Pragma("unroll") for (int k = 0; k < 2; ++k) \
;         acc[ai][bj][m][n] = __builtin_amdgcn_mfma_f32_16x16x32_bf16(Bt[n][k], At[m][k], acc[ai][bj][m][n], 0, 0, 0); __builtin_amdgcn_s_setprio(0); } while (0)
; #define PG8_WAIT_L(n) asm volatile("s_waitcnt lgkmcnt(" #n ")" ::: "memory")
; #define PG8_WAIT_V8_UNLESS(flag) asm volatile("s_cmp_lg_i32 %0, 0\n\ts_cbranch_scc1 .Lpg8rx%=\n\ts_waitcnt vmcnt(8)\n.Lpg8rx%=:" :: "s"(__builtin_amdgcn_readfirstlane(flag)) : "scc", "memory")
; #define PG8_BAR __builtin_amdgcn_s_barrier()
; #define PG8_SCHED __builtin_amdgcn_sched_barrier(0)
; template <class Epi, class Sched, bool ALIGN_EPI = false, bool SP2 = false>
; __device__ __forceinline__ void gemm_phase(PG8_LAS unsigned char* lds, const Gemm g, const Sched& S, const Epi& E) {
;     ...
;             PG8_WAIT_V8_UNLESS(rx); PG8_WAIT_L(0); PG8_BAR; PG8_MMA(0, 0, At, B0); PG8_MMA(0, 1, At, B1); PG8_BAR; PG8_SCHED;
;             PG8_STAGE(PG8_SB(0, 0), b2, voffB); PG8_STAGE(PG8_SB(0, 1), b2 + hstep, voffB); PG8_STAGE(PG8_SA(0, 0), a2, voffA); PG8_SCHED; PG8_LDA(At, 0, 1);
;             PG8_WAIT_V8_UNLESS(rx); PG8_WAIT_L(0); PG8_BAR; PG8_MMA(1, 0, At, B0); PG8_MMA(1, 1, At, B1); PG8_BAR; PG8_SCHED;
.Lpg8rx0:
	s_waitcnt lgkmcnt(0)
	s_setprio 2
	s_barrier
	v_mfma_f32_16x16x32_bf16 v[124:127], v[144:147], v[178:181], v[124:127]
	v_mfma_f32_16x16x32_bf16 v[120:123], v[152:155], v[178:181], v[120:123]
	v_mfma_f32_16x16x32_bf16 v[108:111], v[144:147], v[186:189], v[108:111]
	v_mfma_f32_16x16x32_bf16 v[104:107], v[152:155], v[186:189], v[104:107]
	v_mfma_f32_16x16x32_bf16 v[92:95], v[144:147], v[208:211], v[92:95]
	v_mfma_f32_16x16x32_bf16 v[88:91], v[152:155], v[208:211], v[88:91]
	v_mfma_f32_16x16x32_bf16 v[76:79], v[144:147], v[216:219], v[76:79]
	v_mfma_f32_16x16x32_bf16 v[72:75], v[152:155], v[216:219], v[72:75]
	v_mfma_f32_16x16x32_bf16 v[124:127], v[148:151], v[182:185], v[124:127]
	v_mfma_f32_16x16x32_bf16 v[120:123], v[156:159], v[182:185], v[120:123]
	v_mfma_f32_16x16x32_bf16 v[108:111], v[148:151], v[204:207], v[108:111]
	v_mfma_f32_16x16x32_bf16 v[104:107], v[156:159], v[204:207], v[104:107]
	v_mfma_f32_16x16x32_bf16 v[92:95], v[148:151], v[212:215], v[92:95]
	v_mfma_f32_16x16x32_bf16 v[88:91], v[156:159], v[212:215], v[88:91]
	v_mfma_f32_16x16x32_bf16 v[76:79], v[148:151], v[220:223], v[76:79]
	v_mfma_f32_16x16x32_bf16 v[72:75], v[156:159], v[220:223], v[72:75]
	v_mfma_f32_16x16x32_bf16 v[116:119], v[160:163], v[178:181], v[116:119]
	v_mfma_f32_16x16x32_bf16 v[112:115], v[168:171], v[178:181], v[112:115]
	v_mfma_f32_16x16x32_bf16 v[100:103], v[160:163], v[186:189], v[100:103]
	v_mfma_f32_16x16x32_bf16 v[96:99], v[168:171], v[186:189], v[96:99]
	v_mfma_f32_16x16x32_bf16 v[84:87], v[160:163], v[208:211], v[84:87]
	v_mfma_f32_16x16x32_bf16 v[80:83], v[168:171], v[208:211], v[80:83]
	v_mfma_f32_16x16x32_bf16 v[68:71], v[160:163], v[216:219], v[68:71]
	v_mfma_f32_16x16x32_bf16 v[64:67], v[168:171], v[216:219], v[64:67]
	v_mfma_f32_16x16x32_bf16 v[116:119], v[164:167], v[182:185], v[116:119]
	v_mfma_f32_16x16x32_bf16 v[112:115], v[174:177], v[182:185], v[112:115]
	v_mfma_f32_16x16x32_bf16 v[100:103], v[164:167], v[204:207], v[100:103]
	v_mfma_f32_16x16x32_bf16 v[96:99], v[174:177], v[204:207], v[96:99]
	v_mfma_f32_16x16x32_bf16 v[84:87], v[164:167], v[212:215], v[84:87]
	v_mfma_f32_16x16x32_bf16 v[80:83], v[174:177], v[212:215], v[80:83]
	s_setprio 3
	s_barrier
	v_mfma_f32_16x16x32_bf16 v[68:71], v[164:167], v[220:223], v[68:71]
	v_mfma_f32_16x16x32_bf16 v[64:67], v[174:177], v[220:223], v[64:67]
	s_setprio 0
	ds_read_b128 v[178:181], v173 offset:16384
	ds_read_b128 v[182:185], v173 offset:17408
	ds_read_b128 v[186:189], v173 offset:18432
	ds_read_b128 v[204:207], v173 offset:19456
	ds_read_b128 v[208:211], v173 offset:20480
	ds_read_b128 v[212:215], v173 offset:21504
	ds_read_b128 v[216:219], v173 offset:22528
	ds_read_b128 v[220:223], v173 offset:23552
	s_add_u32 s66, s28, 0x40000
	s_addc_u32 s67, s29, 0
	s_add_i32 m0, s61, s46
	s_nop 0
	global_load_lds_dwordx4 v134, s[28:29]
	s_add_i32 m0, m0, 0x2000
	s_nop 0
	global_load_lds_dwordx4 v138, s[28:29]
	s_add_i32 m0, s65, s46
	s_nop 0
	global_load_lds_dwordx4 v134, s[66:67]
	s_add_i32 m0, m0, 0x2000
	s_nop 0
	global_load_lds_dwordx4 v138, s[66:67]
	s_mov_b32 m0, s9
	s_nop 0
	global_load_lds_dwordx4 v132, s[30:31]
	s_mov_b32 m0, s51
	s_nop 0
	global_load_lds_dwordx4 v136, s[30:31]
	s_cmp_lg_i32 s70, 0
	s_cbranch_scc1 .Lpg8rx1
	s_waitcnt vmcnt(8)
.Lpg8rx1:
	s_waitcnt lgkmcnt(0)
	s_setprio 2
	s_barrier
	v_mfma_f32_16x16x32_bf16 v[60:63], v[144:147], v[178:181], v[60:63]
	v_mfma_f32_16x16x32_bf16 v[56:59], v[152:155], v[178:181], v[56:59]
	v_mfma_f32_16x16x32_bf16 v[44:47], v[144:147], v[186:189], v[44:47]
	v_mfma_f32_16x16x32_bf16 v[40:43], v[152:155], v[186:189], v[40:43]
	v_mfma_f32_16x16x32_bf16 v[28:31], v[144:147], v[208:211], v[28:31]
	v_mfma_f32_16x16x32_bf16 v[24:27], v[152:155], v[208:211], v[24:27]
	v_mfma_f32_16x16x32_bf16 v[12:15], v[144:147], v[216:219], v[12:15]
	v_mfma_f32_16x16x32_bf16 v[8:11], v[152:155], v[216:219], v[8:11]
	v_mfma_f32_16x16x32_bf16 v[60:63], v[148:151], v[182:185], v[60:63]
	v_mfma_f32_16x16x32_bf16 v[56:59], v[156:159], v[182:185], v[56:59]
	v_mfma_f32_16x16x32_bf16 v[44:47], v[148:151], v[204:207], v[44:47]
	v_mfma_f32_16x16x32_bf16 v[40:43], v[156:159], v[204:207], v[40:43]
	v_mfma_f32_16x16x32_bf16 v[28:31], v[148:151], v[212:215], v[28:31]
	v_mfma_f32_16x16x32_bf16 v[24:27], v[156:159], v[212:215], v[24:27]
	v_mfma_f32_16x16x32_bf16 v[12:15], v[148:151], v[220:223], v[12:15]
	v_mfma_f32_16x16x32_bf16 v[8:11], v[156:159], v[220:223], v[8:11]
	v_mfma_f32_16x16x32_bf16 v[52:55], v[160:163], v[178:181], v[52:55]
	v_mfma_f32_16x16x32_bf16 v[48:51], v[168:171], v[178:181], v[48:51]
	v_mfma_f32_16x16x32_bf16 v[36:39], v[160:163], v[186:189], v[36:39]
	v_mfma_f32_16x16x32_bf16 v[32:35], v[168:171], v[186:189], v[32:35]
	v_mfma_f32_16x16x32_bf16 v[20:23], v[160:163], v[208:211], v[20:23]
	v_mfma_f32_16x16x32_bf16 v[16:19], v[168:171], v[208:211], v[16:19]
	v_mfma_f32_16x16x32_bf16 v[4:7], v[160:163], v[216:219], v[4:7]
	v_mfma_f32_16x16x32_bf16 v[0:3], v[168:171], v[216:219], v[0:3]
	v_mfma_f32_16x16x32_bf16 v[52:55], v[164:167], v[182:185], v[52:55]
	v_mfma_f32_16x16x32_bf16 v[48:51], v[174:177], v[182:185], v[48:51]
	v_mfma_f32_16x16x32_bf16 v[36:39], v[164:167], v[204:207], v[36:39]
	v_mfma_f32_16x16x32_bf16 v[32:35], v[174:177], v[204:207], v[32:35]
	v_mfma_f32_16x16x32_bf16 v[20:23], v[164:167], v[212:215], v[20:23]
	v_mfma_f32_16x16x32_bf16 v[16:19], v[174:177], v[212:215], v[16:19]
	s_setprio 3
	s_barrier
; #define PG8_STAGE(bufoff, gbase, voff) do { _Pragma("unroll") for (int _i = 0; _i < 2; ++_i) \
;         __builtin_amdgcn_global_load_lds((const unsigned*)((const char*)(gbase) + (voff)[_i]), (PG8_LAS unsigned*)(lds + (bufoff) + ldsw + _i * 8192), 16, 0, 0); } while (0)
; #define PG8_LDA(dst, b, h) do { _Pragma("unroll") for (int m = 0; m < 4; ++m) _Pragma("unroll") for (int k = 0; k < 2; ++k) dst[m][k] = *(const PG8_LAS bf16x8*)(lds + PG8_SA(b, h) + aoff + m * 2048 + k * 1024); } while (0)
; #define PG8_LDB(dst, b, h) do { _Pragma("unroll") for (int n = 0; n < 2; ++n) _Pragma("unroll") for (int k = 0; k < 2; ++k) dst[n][k] = *(const PG8_LAS bf16x8*)(lds + PG8_SB(b, h) + boff + n * 2048 + k * 1024); } while (0)
; #define PG8_MMA(ai, bj, At, Bt) do { __builtin_amdgcn_s_setprio(1); _Pragma("unroll") for (int m = 0; m < 4; ++m) _Pragma("unroll") for (int n = 0; n < 2; ++n) _Pragma("unroll") for (int k = 0; k < 2; ++k) \
;         acc[ai][bj][m][n] = __builtin_amdgcn_mfma_f32_16x16x32_bf16(Bt[n][k], At[m][k], acc[ai][bj][m][n], 0, 0, 0); __builtin_amdgcn_s_setprio(0); } while (0)
; #define PG8_WAIT_V(n) asm volatile("s_waitcnt vmcnt(" #n ")" ::: "memory")
; #define PG8_WAIT_L(n) asm volatile("s_waitcnt lgkmcnt(" #n ")" ::: "memory")
; #define PG8_WAIT_V8_UNLESS(flag) asm volatile("s_cmp_lg_i32 %0, 0\n\ts_cbranch_scc1 .Lpg8rx%=\n\ts_waitcnt vmcnt(8)\n.Lpg8rx%=:" :: "s"(__builtin_amdgcn_readfirstlane(flag)) : "scc", "memory")
; #define PG8_BAR __builtin_amdgcn_s_barrier()
; template <class Epi, class Sched, bool ALIGN_EPI = false, bool SP2 = false>
; __device__ __forceinline__ void gemm_phase(PG8_LAS unsigned char* lds, const Gemm g, const Sched& S, const Epi& E) {
;     ...
;             PG8_WAIT_V8_UNLESS(rx); PG8_WAIT_L(0); PG8_BAR; PG8_MMA(1, 0, At, B0); PG8_MMA(1, 1, At, B1); PG8_BAR; PG8_SCHED;
;             PG8_STAGE(PG8_SA(0, 1), a2 + hstep, voffA); PG8_SCHED; PG8_LDB(B0, 1, 0); PG8_LDB(B1, 1, 1); PG8_SCHED; PG8_LDA(At, 1, 0);
;             PG8_WAIT_V(8); PG8_WAIT_L(0); PG8_BAR; PG8_MMA(0, 0, At, B0); PG8_MMA(0, 1, At, B1); PG8_BAR; PG8_SCHED;
;             PG8_STAGE(PG8_SB(1, 0), b3, voffB); PG8_STAGE(PG8_SB(1, 1), b3 + hstep, voffB); PG8_STAGE(PG8_SA(1, 0), a3, voffA); PG8_SCHED; PG8_LDA(At, 1, 1);
;             PG8_WAIT_V(8); PG8_WAIT_L(0); PG8_BAR; PG8_MMA(1, 0, At, B0); PG8_MMA(1, 1, At, B1); PG8_BAR; PG8_SCHED;
	v_mfma_f32_16x16x32_bf16 v[4:7], v[164:167], v[220:223], v[4:7]
	v_mfma_f32_16x16x32_bf16 v[0:3], v[174:177], v[220:223], v[0:3]
	s_setprio 0
	s_mov_b64 s[98:99], s[30:31]
	s_add_u32 s100, s30, 0x40000
	s_addc_u32 s101, s31, 0
	s_add_i32 s30, 0, 0x18000
	s_add_i32 s31, 0, 0x1c000
	v_add_u32_e32 v156, s30, v172
	v_add_u32_e32 v174, s31, v172
	ds_read_b128 v[144:147], v156
	ds_read_b128 v[148:151], v156 offset:1024
	ds_read_b128 v[152:155], v156 offset:2048
	ds_read_b128 v[156:159], v156 offset:3072
	ds_read_b128 v[160:163], v174
	ds_read_b128 v[164:167], v174 offset:1024
	ds_read_b128 v[168:171], v174 offset:2048
	ds_read_b128 v[174:177], v174 offset:3072
	ds_read_b128 v[178:181], v173 offset:32768
	ds_read_b128 v[182:185], v173 offset:33792
	ds_read_b128 v[186:189], v173 offset:34816
	ds_read_b128 v[204:207], v173 offset:35840
	ds_read_b128 v[208:211], v173 offset:36864
	ds_read_b128 v[212:215], v173 offset:37888
	ds_read_b128 v[216:219], v173 offset:38912
	ds_read_b128 v[220:223], v173 offset:39936
	s_mov_b32 m0, s52
	s_nop 0
	global_load_lds_dwordx4 v132, s[100:101]
	s_mov_b32 m0, s53
	s_nop 0
	global_load_lds_dwordx4 v136, s[100:101]
	s_waitcnt vmcnt(8)
	s_waitcnt lgkmcnt(0)
	s_setprio 2
	s_barrier
	v_mfma_f32_16x16x32_bf16 v[124:127], v[144:147], v[178:181], v[124:127]
	v_mfma_f32_16x16x32_bf16 v[120:123], v[152:155], v[178:181], v[120:123]
	v_mfma_f32_16x16x32_bf16 v[108:111], v[144:147], v[186:189], v[108:111]
	v_mfma_f32_16x16x32_bf16 v[104:107], v[152:155], v[186:189], v[104:107]
	v_mfma_f32_16x16x32_bf16 v[92:95], v[144:147], v[208:211], v[92:95]
	v_mfma_f32_16x16x32_bf16 v[88:91], v[152:155], v[208:211], v[88:91]
	v_mfma_f32_16x16x32_bf16 v[76:79], v[144:147], v[216:219], v[76:79]
	v_mfma_f32_16x16x32_bf16 v[72:75], v[152:155], v[216:219], v[72:75]
	v_mfma_f32_16x16x32_bf16 v[124:127], v[148:151], v[182:185], v[124:127]
	v_mfma_f32_16x16x32_bf16 v[120:123], v[156:159], v[182:185], v[120:123]
	v_mfma_f32_16x16x32_bf16 v[108:111], v[148:151], v[204:207], v[108:111]
	v_mfma_f32_16x16x32_bf16 v[104:107], v[156:159], v[204:207], v[104:107]
	v_mfma_f32_16x16x32_bf16 v[92:95], v[148:151], v[212:215], v[92:95]
	v_mfma_f32_16x16x32_bf16 v[88:91], v[156:159], v[212:215], v[88:91]
	v_mfma_f32_16x16x32_bf16 v[76:79], v[148:151], v[220:223], v[76:79]
	v_mfma_f32_16x16x32_bf16 v[72:75], v[156:159], v[220:223], v[72:75]
	v_mfma_f32_16x16x32_bf16 v[116:119], v[160:163], v[178:181], v[116:119]
	v_mfma_f32_16x16x32_bf16 v[112:115], v[168:171], v[178:181], v[112:115]
	v_mfma_f32_16x16x32_bf16 v[100:103], v[160:163], v[186:189], v[100:103]
	v_mfma_f32_16x16x32_bf16 v[96:99], v[168:171], v[186:189], v[96:99]
	v_mfma_f32_16x16x32_bf16 v[84:87], v[160:163], v[208:211], v[84:87]
	v_mfma_f32_16x16x32_bf16 v[80:83], v[168:171], v[208:211], v[80:83]
	v_mfma_f32_16x16x32_bf16 v[68:71], v[160:163], v[216:219], v[68:71]
	v_mfma_f32_16x16x32_bf16 v[64:67], v[168:171], v[216:219], v[64:67]
	v_mfma_f32_16x16x32_bf16 v[116:119], v[164:167], v[182:185], v[116:119]
	v_mfma_f32_16x16x32_bf16 v[112:115], v[174:177], v[182:185], v[112:115]
	v_mfma_f32_16x16x32_bf16 v[100:103], v[164:167], v[204:207], v[100:103]
	v_mfma_f32_16x16x32_bf16 v[96:99], v[174:177], v[204:207], v[96:99]
	v_mfma_f32_16x16x32_bf16 v[84:87], v[164:167], v[212:215], v[84:87]
	v_mfma_f32_16x16x32_bf16 v[80:83], v[174:177], v[212:215], v[80:83]
	s_setprio 3
	s_barrier
	v_mfma_f32_16x16x32_bf16 v[68:71], v[164:167], v[220:223], v[68:71]
	v_mfma_f32_16x16x32_bf16 v[64:67], v[174:177], v[220:223], v[64:67]
	s_setprio 0
	ds_read_b128 v[178:181], v173 offset:49152
	ds_read_b128 v[182:185], v173 offset:50176
	ds_read_b128 v[186:189], v173 offset:51200
	ds_read_b128 v[204:207], v173 offset:52224
	ds_read_b128 v[208:211], v173 offset:53248
	ds_read_b128 v[212:215], v173 offset:54272
	ds_read_b128 v[216:219], v173 offset:55296
	ds_read_b128 v[220:223], v173 offset:56320
	s_add_u32 s100, s28, 0x80
	s_addc_u32 s101, s29, 0
	s_add_u32 s28, s28, 0x40080
	s_addc_u32 s29, s29, 0
	s_add_u32 s98, s98, 0x80
	s_addc_u32 s99, s99, 0
	s_add_i32 m0, s30, s46
	s_nop 0
	global_load_lds_dwordx4 v134, s[100:101]
	s_add_i32 m0, m0, 0x2000
	s_nop 0
	global_load_lds_dwordx4 v138, s[100:101]
	s_add_i32 m0, s31, s46
	s_nop 0
	global_load_lds_dwordx4 v134, s[28:29]
	s_add_i32 m0, m0, 0x2000
	s_nop 0
	global_load_lds_dwordx4 v138, s[28:29]
	s_mov_b32 m0, s54
	s_nop 0
	global_load_lds_dwordx4 v132, s[98:99]
	s_mov_b32 m0, s55
	s_nop 0
	global_load_lds_dwordx4 v136, s[98:99]
	s_waitcnt vmcnt(8)
	s_waitcnt lgkmcnt(0)
	s_setprio 2
	s_barrier
	v_mfma_f32_16x16x32_bf16 v[60:63], v[144:147], v[178:181], v[60:63]
	v_mfma_f32_16x16x32_bf16 v[56:59], v[152:155], v[178:181], v[56:59]
	v_mfma_f32_16x16x32_bf16 v[44:47], v[144:147], v[186:189], v[44:47]
	v_mfma_f32_16x16x32_bf16 v[40:43], v[152:155], v[186:189], v[40:43]
	v_mfma_f32_16x16x32_bf16 v[28:31], v[144:147], v[208:211], v[28:31]
	v_mfma_f32_16x16x32_bf16 v[24:27], v[152:155], v[208:211], v[24:27]
	v_mfma_f32_16x16x32_bf16 v[12:15], v[144:147], v[216:219], v[12:15]
	v_mfma_f32_16x16x32_bf16 v[8:11], v[152:155], v[216:219], v[8:11]
	v_mfma_f32_16x16x32_bf16 v[60:63], v[148:151], v[182:185], v[60:63]
	v_mfma_f32_16x16x32_bf16 v[56:59], v[156:159], v[182:185], v[56:59]
	v_mfma_f32_16x16x32_bf16 v[44:47], v[148:151], v[204:207], v[44:47]
	v_mfma_f32_16x16x32_bf16 v[40:43], v[156:159], v[204:207], v[40:43]
	v_mfma_f32_16x16x32_bf16 v[28:31], v[148:151], v[212:215], v[28:31]
	v_mfma_f32_16x16x32_bf16 v[24:27], v[156:159], v[212:215], v[24:27]
	v_mfma_f32_16x16x32_bf16 v[12:15], v[148:151], v[220:223], v[12:15]
	v_mfma_f32_16x16x32_bf16 v[8:11], v[156:159], v[220:223], v[8:11]
	v_mfma_f32_16x16x32_bf16 v[52:55], v[160:163], v[178:181], v[52:55]
	v_mfma_f32_16x16x32_bf16 v[48:51], v[168:171], v[178:181], v[48:51]
	v_mfma_f32_16x16x32_bf16 v[36:39], v[160:163], v[186:189], v[36:39]
	v_mfma_f32_16x16x32_bf16 v[32:35], v[168:171], v[186:189], v[32:35]
	v_mfma_f32_16x16x32_bf16 v[20:23], v[160:163], v[208:211], v[20:23]
	v_mfma_f32_16x16x32_bf16 v[16:19], v[168:171], v[208:211], v[16:19]
	v_mfma_f32_16x16x32_bf16 v[4:7], v[160:163], v[216:219], v[4:7]
	v_mfma_f32_16x16x32_bf16 v[0:3], v[168:171], v[216:219], v[0:3]
	v_mfma_f32_16x16x32_bf16 v[52:55], v[164:167], v[182:185], v[52:55]
	v_mfma_f32_16x16x32_bf16 v[48:51], v[174:177], v[182:185], v[48:51]
	v_mfma_f32_16x16x32_bf16 v[36:39], v[164:167], v[204:207], v[36:39]
	v_mfma_f32_16x16x32_bf16 v[32:35], v[174:177], v[204:207], v[32:35]
	v_mfma_f32_16x16x32_bf16 v[20:23], v[164:167], v[212:215], v[20:23]
	v_mfma_f32_16x16x32_bf16 v[16:19], v[174:177], v[212:215], v[16:19]
	s_setprio 3
	s_barrier
	v_mfma_f32_16x16x32_bf16 v[4:7], v[164:167], v[220:223], v[4:7]
	v_mfma_f32_16x16x32_bf16 v[0:3], v[174:177], v[220:223], v[0:3]
	s_setprio 0
	s_add_i32 s60, s60, 2
	s_add_u32 vcc_lo, vcc_lo, 0x100
	s_addc_u32 vcc_hi, vcc_hi, 0
	s_cmp_gt_u32 s60, 13
	s_cbranch_scc0 .LBB0_148
	s_and_b64 vcc, exec, s[62:63]
	s_cbranch_vccz .LBB0_151
	s_barrier

; #define PG8_STAGE(bufoff, gbase, voff) do { _Pragma("unroll") for (int _i = 0; _i < 2; ++_i) \
;         __builtin_amdgcn_global_load_lds((const unsigned*)((const char*)(gbase) + (voff)[_i]), (PG8_LAS unsigned*)(lds + (bufoff) + ldsw + _i * 8192), 16, 0, 0); } while (0)
; #define PG8_LDA(dst, b, h) do { _Pragma("unroll") for (int m = 0; m < 4; ++m) _Pragma("unroll") for (int k = 0; k < 2; ++k) dst[m][k] = *(const PG8_LAS bf16x8*)(lds + PG8_SA(b, h) + aoff + m * 2048 + k * 1024); } while (0)
; #define PG8_MMA(ai, bj, At, Bt) do { __builtin_amdgcn_s_setprio(1); _Pragma("unroll") for (int m = 0; m < 4; ++m) _Pragma("unroll") for (int n = 0; n < 2; ++n) _Pragma("unroll") for (int k = 0; k < 2; ++k) \
;         acc[ai][bj][m][n] = __builtin_amdgcn_mfma_f32_16x16x32_bf16(Bt[n][k], At[m][k], acc[ai][bj][m][n], 0, 0, 0); __builtin_amdgcn_s_setprio(0); } while (0)
; #define PG8_WAIT_L(n) asm volatile("s_waitcnt lgkmcnt(" #n ")" ::: "memory")
; #define PG8_WAIT_V8_UNLESS(flag) asm volatile("s_cmp_lg_i32 %0, 0\n\ts_cbranch_scc1 .Lpg8rx%=\n\ts_waitcnt vmcnt(8)\n.Lpg8rx%=:" :: "s"(__builtin_amdgcn_readfirstlane(flag)) : "scc", "memory")
; #define PG8_BAR __builtin_amdgcn_s_barrier()
; #define PG8_SCHED __builtin_amdgcn_sched_barrier(0)
; template <class Epi, class Sched, bool ALIGN_EPI = false, bool SP2 = false>
; __device__ __forceinline__ void gemm_phase(PG8_LAS unsigned char* lds, const Gemm g, const Sched& S, const Epi& E) {
;     ...
;             PG8_WAIT_V8_UNLESS(rx); PG8_WAIT_L(0); PG8_BAR; PG8_MMA(0, 0, At, B0); PG8_MMA(0, 1, At, B1); PG8_BAR; PG8_SCHED;
;             PG8_STAGE(PG8_SB(0, 0), b2, voffB); PG8_STAGE(PG8_SB(0, 1), b2 + hstep, voffB); PG8_STAGE(PG8_SA(0, 0), a2, voffA); PG8_SCHED; PG8_LDA(At, 0, 1);
;             PG8_WAIT_V8_UNLESS(rx); PG8_WAIT_L(0); PG8_BAR; PG8_MMA(1, 0, At, B0); PG8_MMA(1, 1, At, B1); PG8_BAR; PG8_SCHED;
.Lpg8rx2:
	s_waitcnt lgkmcnt(0)
	s_setprio 2
	s_barrier
	v_mfma_f32_16x16x32_bf16 v[152:155], v[120:123], v[164:167], v[152:155]
	v_mfma_f32_16x16x32_bf16 v[148:151], v[132:135], v[164:167], v[148:151]
	v_mfma_f32_16x16x32_bf16 v[108:111], v[120:123], v[172:175], v[108:111]
	v_mfma_f32_16x16x32_bf16 v[104:107], v[132:135], v[172:175], v[104:107]
	v_mfma_f32_16x16x32_bf16 v[92:95], v[120:123], v[180:183], v[92:95]
	v_mfma_f32_16x16x32_bf16 v[88:91], v[132:135], v[180:183], v[88:91]
	v_mfma_f32_16x16x32_bf16 v[76:79], v[120:123], v[188:191], v[76:79]
	v_mfma_f32_16x16x32_bf16 v[72:75], v[132:135], v[188:191], v[72:75]
	v_mfma_f32_16x16x32_bf16 v[152:155], v[128:131], v[168:171], v[152:155]
	v_mfma_f32_16x16x32_bf16 v[148:151], v[136:139], v[168:171], v[148:151]
	v_mfma_f32_16x16x32_bf16 v[108:111], v[128:131], v[176:179], v[108:111]
	v_mfma_f32_16x16x32_bf16 v[104:107], v[136:139], v[176:179], v[104:107]
	v_mfma_f32_16x16x32_bf16 v[92:95], v[128:131], v[184:187], v[92:95]
	v_mfma_f32_16x16x32_bf16 v[88:91], v[136:139], v[184:187], v[88:91]
	v_mfma_f32_16x16x32_bf16 v[76:79], v[128:131], v[214:217], v[76:79]
	v_mfma_f32_16x16x32_bf16 v[72:75], v[136:139], v[214:217], v[72:75]
	v_mfma_f32_16x16x32_bf16 v[124:127], v[140:143], v[164:167], v[124:127]
	v_mfma_f32_16x16x32_bf16 v[112:115], v[156:159], v[164:167], v[112:115]
	v_mfma_f32_16x16x32_bf16 v[100:103], v[140:143], v[172:175], v[100:103]
	v_mfma_f32_16x16x32_bf16 v[96:99], v[156:159], v[172:175], v[96:99]
	v_mfma_f32_16x16x32_bf16 v[84:87], v[140:143], v[180:183], v[84:87]
	v_mfma_f32_16x16x32_bf16 v[80:83], v[156:159], v[180:183], v[80:83]
	v_mfma_f32_16x16x32_bf16 v[68:71], v[140:143], v[188:191], v[68:71]
	v_mfma_f32_16x16x32_bf16 v[64:67], v[156:159], v[188:191], v[64:67]
	v_mfma_f32_16x16x32_bf16 v[124:127], v[144:147], v[168:171], v[124:127]
	v_mfma_f32_16x16x32_bf16 v[112:115], v[160:163], v[168:171], v[112:115]
	v_mfma_f32_16x16x32_bf16 v[100:103], v[144:147], v[176:179], v[100:103]
	v_mfma_f32_16x16x32_bf16 v[96:99], v[160:163], v[176:179], v[96:99]
	v_mfma_f32_16x16x32_bf16 v[84:87], v[144:147], v[184:187], v[84:87]
	v_mfma_f32_16x16x32_bf16 v[80:83], v[160:163], v[184:187], v[80:83]
	s_setprio 3
	s_barrier
	v_mfma_f32_16x16x32_bf16 v[68:71], v[144:147], v[214:217], v[68:71]
	v_mfma_f32_16x16x32_bf16 v[64:67], v[160:163], v[214:217], v[64:67]
	s_setprio 0
	ds_read_b128 v[164:167], v248 offset:16384
	ds_read_b128 v[168:171], v248 offset:17408
	ds_read_b128 v[172:175], v248 offset:18432
	ds_read_b128 v[176:179], v248 offset:19456
	ds_read_b128 v[180:183], v248 offset:20480
	ds_read_b128 v[184:187], v248 offset:21504
	ds_read_b128 v[188:191], v248 offset:22528
	ds_read_b128 v[214:217], v248 offset:23552
	s_add_u32 s60, s28, 0x40000
	s_addc_u32 s61, s29, 0
	s_add_i32 m0, s59, s39
	s_nop 0
	global_load_lds_dwordx4 v194, s[28:29]
	s_add_i32 m0, m0, 0x2000
	s_nop 0
	global_load_lds_dwordx4 v208, s[28:29]
	s_add_i32 m0, s65, s39
	s_nop 0
	global_load_lds_dwordx4 v194, s[60:61]
	s_add_i32 m0, m0, 0x2000
	s_nop 0
	global_load_lds_dwordx4 v208, s[60:61]
	s_mov_b32 m0, s41
	s_nop 0
	global_load_lds_dwordx4 v204, s[30:31]
	s_mov_b32 m0, s44
	s_nop 0
	global_load_lds_dwordx4 v206, s[30:31]
	s_cmp_lg_i32 s66, 0
	s_cbranch_scc1 .Lpg8rx3
	s_waitcnt vmcnt(8)
.Lpg8rx3:
	s_waitcnt lgkmcnt(0)
	s_setprio 2
	s_barrier
	v_mfma_f32_16x16x32_bf16 v[60:63], v[120:123], v[164:167], v[60:63]
	v_mfma_f32_16x16x32_bf16 v[56:59], v[132:135], v[164:167], v[56:59]
	v_mfma_f32_16x16x32_bf16 v[44:47], v[120:123], v[172:175], v[44:47]
	v_mfma_f32_16x16x32_bf16 v[40:43], v[132:135], v[172:175], v[40:43]
	v_mfma_f32_16x16x32_bf16 v[28:31], v[120:123], v[180:183], v[28:31]
	v_mfma_f32_16x16x32_bf16 v[24:27], v[132:135], v[180:183], v[24:27]
	v_mfma_f32_16x16x32_bf16 v[12:15], v[120:123], v[188:191], v[12:15]
	v_mfma_f32_16x16x32_bf16 v[8:11], v[132:135], v[188:191], v[8:11]
	v_mfma_f32_16x16x32_bf16 v[60:63], v[128:131], v[168:171], v[60:63]
	v_mfma_f32_16x16x32_bf16 v[56:59], v[136:139], v[168:171], v[56:59]
	v_mfma_f32_16x16x32_bf16 v[44:47], v[128:131], v[176:179], v[44:47]
	v_mfma_f32_16x16x32_bf16 v[40:43], v[136:139], v[176:179], v[40:43]
	v_mfma_f32_16x16x32_bf16 v[28:31], v[128:131], v[184:187], v[28:31]
	v_mfma_f32_16x16x32_bf16 v[24:27], v[136:139], v[184:187], v[24:27]
	v_mfma_f32_16x16x32_bf16 v[12:15], v[128:131], v[214:217], v[12:15]
	v_mfma_f32_16x16x32_bf16 v[8:11], v[136:139], v[214:217], v[8:11]
	v_mfma_f32_16x16x32_bf16 v[52:55], v[140:143], v[164:167], v[52:55]
	v_mfma_f32_16x16x32_bf16 v[48:51], v[156:159], v[164:167], v[48:51]
	v_mfma_f32_16x16x32_bf16 v[36:39], v[140:143], v[172:175], v[36:39]
	v_mfma_f32_16x16x32_bf16 v[32:35], v[156:159], v[172:175], v[32:35]
	v_mfma_f32_16x16x32_bf16 v[20:23], v[140:143], v[180:183], v[20:23]
	v_mfma_f32_16x16x32_bf16 v[16:19], v[156:159], v[180:183], v[16:19]
	v_mfma_f32_16x16x32_bf16 v[4:7], v[140:143], v[188:191], v[4:7]
	v_mfma_f32_16x16x32_bf16 v[0:3], v[156:159], v[188:191], v[0:3]
	v_mfma_f32_16x16x32_bf16 v[52:55], v[144:147], v[168:171], v[52:55]
	v_mfma_f32_16x16x32_bf16 v[48:51], v[160:163], v[168:171], v[48:51]
	v_mfma_f32_16x16x32_bf16 v[36:39], v[144:147], v[176:179], v[36:39]
	v_mfma_f32_16x16x32_bf16 v[32:35], v[160:163], v[176:179], v[32:35]
	v_mfma_f32_16x16x32_bf16 v[20:23], v[144:147], v[184:187], v[20:23]
	v_mfma_f32_16x16x32_bf16 v[16:19], v[160:163], v[184:187], v[16:19]
	s_setprio 3
	s_barrier
; #define PG8_STAGE(bufoff, gbase, voff) do { _Pragma("unroll") for (int _i = 0; _i < 2; ++_i) \
;         __builtin_amdgcn_global_load_lds((const unsigned*)((const char*)(gbase) + (voff)[_i]), (PG8_LAS unsigned*)(lds + (bufoff) + ldsw + _i * 8192), 16, 0, 0); } while (0)
; #define PG8_LDA(dst, b, h) do { _Pragma("unroll") for (int m = 0; m < 4; ++m) _Pragma("unroll") for (int k = 0; k < 2; ++k) dst[m][k] = *(const PG8_LAS bf16x8*)(lds + PG8_SA(b, h) + aoff + m * 2048 + k * 1024); } while (0)
; #define PG8_LDB(dst, b, h) do { _Pragma("unroll") for (int n = 0; n < 2; ++n) _Pragma("unroll") for (int k = 0; k < 2; ++k) dst[n][k] = *(const PG8_LAS bf16x8*)(lds + PG8_SB(b, h) + boff + n * 2048 + k * 1024); } while (0)
; #define PG8_MMA(ai, bj, At, Bt) do { __builtin_amdgcn_s_setprio(1); _Pragma("unroll") for (int m = 0; m < 4; ++m) _Pragma("unroll") for (int n = 0; n < 2; ++n) _Pragma("unroll") for (int k = 0; k < 2; ++k) \
;         acc[ai][bj][m][n] = __builtin_amdgcn_mfma_f32_16x16x32_bf16(Bt[n][k], At[m][k], acc[ai][bj][m][n], 0, 0, 0); __builtin_amdgcn_s_setprio(0); } while (0)
; #define PG8_WAIT_V(n) asm volatile("s_waitcnt vmcnt(" #n ")" ::: "memory")
; #define PG8_WAIT_L(n) asm volatile("s_waitcnt lgkmcnt(" #n ")" ::: "memory")
; #define PG8_WAIT_V8_UNLESS(flag) asm volatile("s_cmp_lg_i32 %0, 0\n\ts_cbranch_scc1 .Lpg8rx%=\n\ts_waitcnt vmcnt(8)\n.Lpg8rx%=:" :: "s"(__builtin_amdgcn_readfirstlane(flag)) : "scc", "memory")
; #define PG8_BAR __builtin_amdgcn_s_barrier()
; template <class Epi, class Sched, bool ALIGN_EPI = false, bool SP2 = false>
; __device__ __forceinline__ void gemm_phase(PG8_LAS unsigned char* lds, const Gemm g, const Sched& S, const Epi& E) {
;     ...
;             PG8_WAIT_V8_UNLESS(rx); PG8_WAIT_L(0); PG8_BAR; PG8_MMA(1, 0, At, B0); PG8_MMA(1, 1, At, B1); PG8_BAR; PG8_SCHED;
;             PG8_STAGE(PG8_SA(0, 1), a2 + hstep, voffA); PG8_SCHED; PG8_LDB(B0, 1, 0); PG8_LDB(B1, 1, 1); PG8_SCHED; PG8_LDA(At, 1, 0);
;             PG8_WAIT_V(8); PG8_WAIT_L(0); PG8_BAR; PG8_MMA(0, 0, At, B0); PG8_MMA(0, 1, At, B1); PG8_BAR; PG8_SCHED;
;             PG8_STAGE(PG8_SB(1, 0), b3, voffB); PG8_STAGE(PG8_SB(1, 1), b3 + hstep, voffB); PG8_STAGE(PG8_SA(1, 0), a3, voffA); PG8_SCHED; PG8_LDA(At, 1, 1);
;             PG8_WAIT_V(8); PG8_WAIT_L(0); PG8_BAR; PG8_MMA(1, 0, At, B0); PG8_MMA(1, 1, At, B1); PG8_BAR; PG8_SCHED;
	v_mfma_f32_16x16x32_bf16 v[4:7], v[144:147], v[214:217], v[4:7]
	v_mfma_f32_16x16x32_bf16 v[0:3], v[160:163], v[214:217], v[0:3]
	s_setprio 0
	s_mov_b64 s[98:99], s[30:31]
	s_add_u32 s100, s30, 0x40000
	s_addc_u32 s101, s31, 0
	s_add_i32 s30, 0, 0x18000
	s_add_i32 s31, 0, 0x1c000
	v_add_u32_e32 v136, s30, v247
	v_add_u32_e32 v160, s31, v247
	ds_read_b128 v[120:123], v136
	ds_read_b128 v[128:131], v136 offset:1024
	ds_read_b128 v[132:135], v136 offset:2048
	ds_read_b128 v[136:139], v136 offset:3072
	ds_read_b128 v[140:143], v160
	ds_read_b128 v[144:147], v160 offset:1024
	ds_read_b128 v[156:159], v160 offset:2048
	ds_read_b128 v[160:163], v160 offset:3072
	ds_read_b128 v[164:167], v248 offset:32768
	ds_read_b128 v[168:171], v248 offset:33792
	ds_read_b128 v[172:175], v248 offset:34816
	ds_read_b128 v[176:179], v248 offset:35840
	ds_read_b128 v[180:183], v248 offset:36864
	ds_read_b128 v[184:187], v248 offset:37888
	ds_read_b128 v[188:191], v248 offset:38912
	ds_read_b128 v[214:217], v248 offset:39936
	s_mov_b32 m0, s46
	s_nop 0
	global_load_lds_dwordx4 v204, s[100:101]
	s_mov_b32 m0, s48
	s_nop 0
	global_load_lds_dwordx4 v206, s[100:101]
	s_waitcnt vmcnt(8)
	s_waitcnt lgkmcnt(0)
	s_setprio 2
	s_barrier
	v_mfma_f32_16x16x32_bf16 v[152:155], v[120:123], v[164:167], v[152:155]
	v_mfma_f32_16x16x32_bf16 v[148:151], v[132:135], v[164:167], v[148:151]
	v_mfma_f32_16x16x32_bf16 v[108:111], v[120:123], v[172:175], v[108:111]
	v_mfma_f32_16x16x32_bf16 v[104:107], v[132:135], v[172:175], v[104:107]
	v_mfma_f32_16x16x32_bf16 v[92:95], v[120:123], v[180:183], v[92:95]
	v_mfma_f32_16x16x32_bf16 v[88:91], v[132:135], v[180:183], v[88:91]
	v_mfma_f32_16x16x32_bf16 v[76:79], v[120:123], v[188:191], v[76:79]
	v_mfma_f32_16x16x32_bf16 v[72:75], v[132:135], v[188:191], v[72:75]
	v_mfma_f32_16x16x32_bf16 v[152:155], v[128:131], v[168:171], v[152:155]
	v_mfma_f32_16x16x32_bf16 v[148:151], v[136:139], v[168:171], v[148:151]
	v_mfma_f32_16x16x32_bf16 v[108:111], v[128:131], v[176:179], v[108:111]
	v_mfma_f32_16x16x32_bf16 v[104:107], v[136:139], v[176:179], v[104:107]
	v_mfma_f32_16x16x32_bf16 v[92:95], v[128:131], v[184:187], v[92:95]
	v_mfma_f32_16x16x32_bf16 v[88:91], v[136:139], v[184:187], v[88:91]
	v_mfma_f32_16x16x32_bf16 v[76:79], v[128:131], v[214:217], v[76:79]
	v_mfma_f32_16x16x32_bf16 v[72:75], v[136:139], v[214:217], v[72:75]
	v_mfma_f32_16x16x32_bf16 v[124:127], v[140:143], v[164:167], v[124:127]
	v_mfma_f32_16x16x32_bf16 v[112:115], v[156:159], v[164:167], v[112:115]
	v_mfma_f32_16x16x32_bf16 v[100:103], v[140:143], v[172:175], v[100:103]
	v_mfma_f32_16x16x32_bf16 v[96:99], v[156:159], v[172:175], v[96:99]
	v_mfma_f32_16x16x32_bf16 v[84:87], v[140:143], v[180:183], v[84:87]
	v_mfma_f32_16x16x32_bf16 v[80:83], v[156:159], v[180:183], v[80:83]
	v_mfma_f32_16x16x32_bf16 v[68:71], v[140:143], v[188:191], v[68:71]
	v_mfma_f32_16x16x32_bf16 v[64:67], v[156:159], v[188:191], v[64:67]
	v_mfma_f32_16x16x32_bf16 v[124:127], v[144:147], v[168:171], v[124:127]
	v_mfma_f32_16x16x32_bf16 v[112:115], v[160:163], v[168:171], v[112:115]
	v_mfma_f32_16x16x32_bf16 v[100:103], v[144:147], v[176:179], v[100:103]
	v_mfma_f32_16x16x32_bf16 v[96:99], v[160:163], v[176:179], v[96:99]
	v_mfma_f32_16x16x32_bf16 v[84:87], v[144:147], v[184:187], v[84:87]
	v_mfma_f32_16x16x32_bf16 v[80:83], v[160:163], v[184:187], v[80:83]
	s_setprio 3
	s_barrier
	v_mfma_f32_16x16x32_bf16 v[68:71], v[144:147], v[214:217], v[68:71]
	v_mfma_f32_16x16x32_bf16 v[64:67], v[160:163], v[214:217], v[64:67]
	s_setprio 0
	ds_read_b128 v[164:167], v248 offset:49152
	ds_read_b128 v[168:171], v248 offset:50176
	ds_read_b128 v[172:175], v248 offset:51200
	ds_read_b128 v[176:179], v248 offset:52224
	ds_read_b128 v[180:183], v248 offset:53248
	ds_read_b128 v[184:187], v248 offset:54272
	ds_read_b128 v[188:191], v248 offset:55296
	ds_read_b128 v[214:217], v248 offset:56320
	s_add_u32 s100, s28, 0x80
	s_addc_u32 s101, s29, 0
	s_add_u32 s28, s28, 0x40080
	s_addc_u32 s29, s29, 0
	s_add_u32 s98, s98, 0x80
	s_addc_u32 s99, s99, 0
	s_add_i32 m0, s30, s39
	s_nop 0
	global_load_lds_dwordx4 v194, s[100:101]
	s_add_i32 m0, m0, 0x2000
	s_nop 0
	global_load_lds_dwordx4 v208, s[100:101]
	s_add_i32 m0, s31, s39
	s_nop 0
	global_load_lds_dwordx4 v194, s[28:29]
	s_add_i32 m0, m0, 0x2000
	s_nop 0
	global_load_lds_dwordx4 v208, s[28:29]
	s_mov_b32 m0, s50
	s_nop 0
	global_load_lds_dwordx4 v204, s[98:99]
	s_mov_b32 m0, s51
	s_nop 0
	global_load_lds_dwordx4 v206, s[98:99]
	s_waitcnt vmcnt(8)
	s_waitcnt lgkmcnt(0)
	s_setprio 2
	s_barrier
	v_mfma_f32_16x16x32_bf16 v[60:63], v[120:123], v[164:167], v[60:63]
	v_mfma_f32_16x16x32_bf16 v[56:59], v[132:135], v[164:167], v[56:59]
	v_mfma_f32_16x16x32_bf16 v[44:47], v[120:123], v[172:175], v[44:47]
	v_mfma_f32_16x16x32_bf16 v[40:43], v[132:135], v[172:175], v[40:43]
	v_mfma_f32_16x16x32_bf16 v[28:31], v[120:123], v[180:183], v[28:31]
	v_mfma_f32_16x16x32_bf16 v[24:27], v[132:135], v[180:183], v[24:27]
	v_mfma_f32_16x16x32_bf16 v[12:15], v[120:123], v[188:191], v[12:15]
	v_mfma_f32_16x16x32_bf16 v[8:11], v[132:135], v[188:191], v[8:11]
	v_mfma_f32_16x16x32_bf16 v[60:63], v[128:131], v[168:171], v[60:63]
	v_mfma_f32_16x16x32_bf16 v[56:59], v[136:139], v[168:171], v[56:59]
	v_mfma_f32_16x16x32_bf16 v[44:47], v[128:131], v[176:179], v[44:47]
	v_mfma_f32_16x16x32_bf16 v[40:43], v[136:139], v[176:179], v[40:43]
	v_mfma_f32_16x16x32_bf16 v[28:31], v[128:131], v[184:187], v[28:31]
	v_mfma_f32_16x16x32_bf16 v[24:27], v[136:139], v[184:187], v[24:27]
	v_mfma_f32_16x16x32_bf16 v[12:15], v[128:131], v[214:217], v[12:15]
	v_mfma_f32_16x16x32_bf16 v[8:11], v[136:139], v[214:217], v[8:11]
	v_mfma_f32_16x16x32_bf16 v[52:55], v[140:143], v[164:167], v[52:55]
	v_mfma_f32_16x16x32_bf16 v[48:51], v[156:159], v[164:167], v[48:51]
	v_mfma_f32_16x16x32_bf16 v[36:39], v[140:143], v[172:175], v[36:39]
	v_mfma_f32_16x16x32_bf16 v[32:35], v[156:159], v[172:175], v[32:35]
	v_mfma_f32_16x16x32_bf16 v[20:23], v[140:143], v[180:183], v[20:23]
	v_mfma_f32_16x16x32_bf16 v[16:19], v[156:159], v[180:183], v[16:19]
	v_mfma_f32_16x16x32_bf16 v[4:7], v[140:143], v[188:191], v[4:7]
	v_mfma_f32_16x16x32_bf16 v[0:3], v[156:159], v[188:191], v[0:3]
	v_mfma_f32_16x16x32_bf16 v[52:55], v[144:147], v[168:171], v[52:55]
	v_mfma_f32_16x16x32_bf16 v[48:51], v[160:163], v[168:171], v[48:51]
	v_mfma_f32_16x16x32_bf16 v[36:39], v[144:147], v[176:179], v[36:39]
	v_mfma_f32_16x16x32_bf16 v[32:35], v[160:163], v[176:179], v[32:35]
	v_mfma_f32_16x16x32_bf16 v[20:23], v[144:147], v[184:187], v[20:23]
	v_mfma_f32_16x16x32_bf16 v[16:19], v[160:163], v[184:187], v[16:19]
	s_setprio 3
	s_barrier
	v_mfma_f32_16x16x32_bf16 v[4:7], v[144:147], v[214:217], v[4:7]
	v_mfma_f32_16x16x32_bf16 v[0:3], v[160:163], v[214:217], v[0:3]
	s_setprio 0
	s_add_i32 s58, s58, 2
	s_add_u32 s62, s62, 0x100
	s_addc_u32 s63, s63, 0
	s_cmp_gt_u32 s58, 13
	s_cbranch_scc0 .LBB0_514
	s_and_b64 vcc, exec, s[14:15]
	s_cbranch_vccz .LBB0_517
	s_barrier

; #define PG8_STAGE(bufoff, gbase, voff) do { _Pragma("unroll") for (int _i = 0; _i < 2; ++_i) \
;         __builtin_amdgcn_global_load_lds((const unsigned*)((const char*)(gbase) + (voff)[_i]), (PG8_LAS unsigned*)(lds + (bufoff) + ldsw + _i * 8192), 16, 0, 0); } while (0)
; #define PG8_LDA(dst, b, h) do { _Pragma("unroll") for (int m = 0; m < 4; ++m) _Pragma("unroll") for (int k = 0; k < 2; ++k) dst[m][k] = *(const PG8_LAS bf16x8*)(lds + PG8_SA(b, h) + aoff + m * 2048 + k * 1024); } while (0)
; #define PG8_MMA(ai, bj, At, Bt) do { __builtin_amdgcn_s_setprio(1); _Pragma("unroll") for (int m = 0; m < 4; ++m) _Pragma("unroll") for (int n = 0; n < 2; ++n) _Pragma("unroll") for (int k = 0; k < 2; ++k) \
;         acc[ai][bj][m][n] = __builtin_amdgcn_mfma_f32_16x16x32_bf16(Bt[n][k], At[m][k], acc[ai][bj][m][n], 0, 0, 0); __builtin_amdgcn_s_setprio(0); } while (0)
; #define PG8_WAIT_L(n) asm volatile("s_waitcnt lgkmcnt(" #n ")" ::: "memory")
; #define PG8_WAIT_V8_UNLESS(flag) asm volatile("s_cmp_lg_i32 %0, 0\n\ts_cbranch_scc1 .Lpg8rx%=\n\ts_waitcnt vmcnt(8)\n.Lpg8rx%=:" :: "s"(__builtin_amdgcn_readfirstlane(flag)) : "scc", "memory")
; #define PG8_BAR __builtin_amdgcn_s_barrier()
; #define PG8_SCHED __builtin_amdgcn_sched_barrier(0)
; template <class Epi, class Sched, bool ALIGN_EPI = false, bool SP2 = false>
; __device__ __forceinline__ void gemm_phase(PG8_LAS unsigned char* lds, const Gemm g, const Sched& S, const Epi& E) {
;     ...
;             PG8_WAIT_V8_UNLESS(rx); PG8_WAIT_L(0); PG8_BAR; PG8_MMA(0, 0, At, B0); PG8_MMA(0, 1, At, B1); PG8_BAR; PG8_SCHED;
;             PG8_STAGE(PG8_SB(0, 0), b2, voffB); PG8_STAGE(PG8_SB(0, 1), b2 + hstep, voffB); PG8_STAGE(PG8_SA(0, 0), a2, voffA); PG8_SCHED; PG8_LDA(At, 0, 1);
;             PG8_WAIT_V8_UNLESS(rx); PG8_WAIT_L(0); PG8_BAR; PG8_MMA(1, 0, At, B0); PG8_MMA(1, 1, At, B1); PG8_BAR; PG8_SCHED;
.Lpg8rx4:
	s_waitcnt lgkmcnt(0)
	s_setprio 2
	s_barrier
	v_mfma_f32_16x16x32_bf16 v[124:127], v[132:135], v[176:179], v[124:127]
	v_mfma_f32_16x16x32_bf16 v[120:123], v[140:143], v[176:179], v[120:123]
	v_mfma_f32_16x16x32_bf16 v[108:111], v[132:135], v[204:207], v[108:111]
	v_mfma_f32_16x16x32_bf16 v[104:107], v[140:143], v[204:207], v[104:107]
	v_mfma_f32_16x16x32_bf16 v[92:95], v[132:135], v[212:215], v[92:95]
	v_mfma_f32_16x16x32_bf16 v[88:91], v[140:143], v[212:215], v[88:91]
	v_mfma_f32_16x16x32_bf16 v[76:79], v[132:135], v[220:223], v[76:79]
	v_mfma_f32_16x16x32_bf16 v[72:75], v[140:143], v[220:223], v[72:75]
	v_mfma_f32_16x16x32_bf16 v[124:127], v[136:139], v[186:189], v[124:127]
	v_mfma_f32_16x16x32_bf16 v[120:123], v[144:147], v[186:189], v[120:123]
	v_mfma_f32_16x16x32_bf16 v[108:111], v[136:139], v[208:211], v[108:111]
	v_mfma_f32_16x16x32_bf16 v[104:107], v[144:147], v[208:211], v[104:107]
	v_mfma_f32_16x16x32_bf16 v[92:95], v[136:139], v[216:219], v[92:95]
	v_mfma_f32_16x16x32_bf16 v[88:91], v[144:147], v[216:219], v[88:91]
	v_mfma_f32_16x16x32_bf16 v[76:79], v[136:139], v[224:227], v[76:79]
	v_mfma_f32_16x16x32_bf16 v[72:75], v[144:147], v[224:227], v[72:75]
	v_mfma_f32_16x16x32_bf16 v[116:119], v[148:151], v[176:179], v[116:119]
	v_mfma_f32_16x16x32_bf16 v[112:115], v[168:171], v[176:179], v[112:115]
	v_mfma_f32_16x16x32_bf16 v[100:103], v[148:151], v[204:207], v[100:103]
	v_mfma_f32_16x16x32_bf16 v[96:99], v[168:171], v[204:207], v[96:99]
	v_mfma_f32_16x16x32_bf16 v[84:87], v[148:151], v[212:215], v[84:87]
	v_mfma_f32_16x16x32_bf16 v[80:83], v[168:171], v[212:215], v[80:83]
	v_mfma_f32_16x16x32_bf16 v[68:71], v[148:151], v[220:223], v[68:71]
	v_mfma_f32_16x16x32_bf16 v[64:67], v[168:171], v[220:223], v[64:67]
	v_mfma_f32_16x16x32_bf16 v[116:119], v[164:167], v[186:189], v[116:119]
	v_mfma_f32_16x16x32_bf16 v[112:115], v[172:175], v[186:189], v[112:115]
	v_mfma_f32_16x16x32_bf16 v[100:103], v[164:167], v[208:211], v[100:103]
	v_mfma_f32_16x16x32_bf16 v[96:99], v[172:175], v[208:211], v[96:99]
	v_mfma_f32_16x16x32_bf16 v[84:87], v[164:167], v[216:219], v[84:87]
	v_mfma_f32_16x16x32_bf16 v[80:83], v[172:175], v[216:219], v[80:83]
	s_setprio 3
	s_barrier
	v_mfma_f32_16x16x32_bf16 v[68:71], v[164:167], v[224:227], v[68:71]
	v_mfma_f32_16x16x32_bf16 v[64:67], v[172:175], v[224:227], v[64:67]
	s_setprio 0
	ds_read_b128 v[176:179], v185 offset:16384
	ds_read_b128 v[186:189], v185 offset:17408
	ds_read_b128 v[204:207], v185 offset:18432
	ds_read_b128 v[208:211], v185 offset:19456
	ds_read_b128 v[212:215], v185 offset:20480
	ds_read_b128 v[216:219], v185 offset:21504
	ds_read_b128 v[220:223], v185 offset:22528
	ds_read_b128 v[224:227], v185 offset:23552
	s_add_u32 s60, s28, 0x40000
	s_addc_u32 s61, s29, 0
	s_add_i32 m0, s59, s38
	s_nop 0
	global_load_lds_dwordx4 v154, s[28:29]
	s_add_i32 m0, m0, 0x2000
	s_nop 0
	global_load_lds_dwordx4 v158, s[28:29]
	s_add_i32 m0, s62, s38
	s_nop 0
	global_load_lds_dwordx4 v154, s[60:61]
	s_add_i32 m0, m0, 0x2000
	s_nop 0
	global_load_lds_dwordx4 v158, s[60:61]
	s_mov_b32 m0, s21
	s_nop 0
	global_load_lds_dwordx4 v152, s[30:31]
	s_mov_b32 m0, s23
	s_nop 0
	global_load_lds_dwordx4 v156, s[30:31]
	s_cmp_lg_i32 s63, 0
	s_cbranch_scc1 .Lpg8rx5
	s_waitcnt vmcnt(8)
.Lpg8rx5:
	s_waitcnt lgkmcnt(0)
	s_setprio 2
	s_barrier
	v_mfma_f32_16x16x32_bf16 v[60:63], v[132:135], v[176:179], v[60:63]
	v_mfma_f32_16x16x32_bf16 v[56:59], v[140:143], v[176:179], v[56:59]
	v_mfma_f32_16x16x32_bf16 v[44:47], v[132:135], v[204:207], v[44:47]
	v_mfma_f32_16x16x32_bf16 v[40:43], v[140:143], v[204:207], v[40:43]
	v_mfma_f32_16x16x32_bf16 v[28:31], v[132:135], v[212:215], v[28:31]
	v_mfma_f32_16x16x32_bf16 v[24:27], v[140:143], v[212:215], v[24:27]
	v_mfma_f32_16x16x32_bf16 v[12:15], v[132:135], v[220:223], v[12:15]
	v_mfma_f32_16x16x32_bf16 v[8:11], v[140:143], v[220:223], v[8:11]
	v_mfma_f32_16x16x32_bf16 v[60:63], v[136:139], v[186:189], v[60:63]
	v_mfma_f32_16x16x32_bf16 v[56:59], v[144:147], v[186:189], v[56:59]
	v_mfma_f32_16x16x32_bf16 v[44:47], v[136:139], v[208:211], v[44:47]
	v_mfma_f32_16x16x32_bf16 v[40:43], v[144:147], v[208:211], v[40:43]
	v_mfma_f32_16x16x32_bf16 v[28:31], v[136:139], v[216:219], v[28:31]
	v_mfma_f32_16x16x32_bf16 v[24:27], v[144:147], v[216:219], v[24:27]
	v_mfma_f32_16x16x32_bf16 v[12:15], v[136:139], v[224:227], v[12:15]
	v_mfma_f32_16x16x32_bf16 v[8:11], v[144:147], v[224:227], v[8:11]
	v_mfma_f32_16x16x32_bf16 v[52:55], v[148:151], v[176:179], v[52:55]
	v_mfma_f32_16x16x32_bf16 v[48:51], v[168:171], v[176:179], v[48:51]
	v_mfma_f32_16x16x32_bf16 v[36:39], v[148:151], v[204:207], v[36:39]
	v_mfma_f32_16x16x32_bf16 v[32:35], v[168:171], v[204:207], v[32:35]
	v_mfma_f32_16x16x32_bf16 v[20:23], v[148:151], v[212:215], v[20:23]
	v_mfma_f32_16x16x32_bf16 v[16:19], v[168:171], v[212:215], v[16:19]
	v_mfma_f32_16x16x32_bf16 v[4:7], v[148:151], v[220:223], v[4:7]
	v_mfma_f32_16x16x32_bf16 v[0:3], v[168:171], v[220:223], v[0:3]
	v_mfma_f32_16x16x32_bf16 v[52:55], v[164:167], v[186:189], v[52:55]
	v_mfma_f32_16x16x32_bf16 v[48:51], v[172:175], v[186:189], v[48:51]
	v_mfma_f32_16x16x32_bf16 v[36:39], v[164:167], v[208:211], v[36:39]
	v_mfma_f32_16x16x32_bf16 v[32:35], v[172:175], v[208:211], v[32:35]
	v_mfma_f32_16x16x32_bf16 v[20:23], v[164:167], v[216:219], v[20:23]
	v_mfma_f32_16x16x32_bf16 v[16:19], v[172:175], v[216:219], v[16:19]
	s_setprio 3
	s_barrier
; #define PG8_STAGE(bufoff, gbase, voff) do { _Pragma("unroll") for (int _i = 0; _i < 2; ++_i) \
;         __builtin_amdgcn_global_load_lds((const unsigned*)((const char*)(gbase) + (voff)[_i]), (PG8_LAS unsigned*)(lds + (bufoff) + ldsw + _i * 8192), 16, 0, 0); } while (0)
; #define PG8_LDA(dst, b, h) do { _Pragma("unroll") for (int m = 0; m < 4; ++m) _Pragma("unroll") for (int k = 0; k < 2; ++k) dst[m][k] = *(const PG8_LAS bf16x8*)(lds + PG8_SA(b, h) + aoff + m * 2048 + k * 1024); } while (0)
; #define PG8_LDB(dst, b, h) do { _Pragma("unroll") for (int n = 0; n < 2; ++n) _Pragma("unroll") for (int k = 0; k < 2; ++k) dst[n][k] = *(const PG8_LAS bf16x8*)(lds + PG8_SB(b, h) + boff + n * 2048 + k * 1024); } while (0)
; #define PG8_MMA(ai, bj, At, Bt) do { __builtin_amdgcn_s_setprio(1); _Pragma("unroll") for (int m = 0; m < 4; ++m) _Pragma("unroll") for (int n = 0; n < 2; ++n) _Pragma("unroll") for (int k = 0; k < 2; ++k) \
;         acc[ai][bj][m][n] = __builtin_amdgcn_mfma_f32_16x16x32_bf16(Bt[n][k], At[m][k], acc[ai][bj][m][n], 0, 0, 0); __builtin_amdgcn_s_setprio(0); } while (0)
; #define PG8_WAIT_V(n) asm volatile("s_waitcnt vmcnt(" #n ")" ::: "memory")
; #define PG8_WAIT_L(n) asm volatile("s_waitcnt lgkmcnt(" #n ")" ::: "memory")
; #define PG8_WAIT_V8_UNLESS(flag) asm volatile("s_cmp_lg_i32 %0, 0\n\ts_cbranch_scc1 .Lpg8rx%=\n\ts_waitcnt vmcnt(8)\n.Lpg8rx%=:" :: "s"(__builtin_amdgcn_readfirstlane(flag)) : "scc", "memory")
; #define PG8_BAR __builtin_amdgcn_s_barrier()
; template <class Epi, class Sched, bool ALIGN_EPI = false, bool SP2 = false>
; __device__ __forceinline__ void gemm_phase(PG8_LAS unsigned char* lds, const Gemm g, const Sched& S, const Epi& E) {
;     ...
;             PG8_WAIT_V8_UNLESS(rx); PG8_WAIT_L(0); PG8_BAR; PG8_MMA(1, 0, At, B0); PG8_MMA(1, 1, At, B1); PG8_BAR; PG8_SCHED;
;             PG8_STAGE(PG8_SA(0, 1), a2 + hstep, voffA); PG8_SCHED; PG8_LDB(B0, 1, 0); PG8_LDB(B1, 1, 1); PG8_SCHED; PG8_LDA(At, 1, 0);
;             PG8_WAIT_V(8); PG8_WAIT_L(0); PG8_BAR; PG8_MMA(0, 0, At, B0); PG8_MMA(0, 1, At, B1); PG8_BAR; PG8_SCHED;
;             PG8_STAGE(PG8_SB(1, 0), b3, voffB); PG8_STAGE(PG8_SB(1, 1), b3 + hstep, voffB); PG8_STAGE(PG8_SA(1, 0), a3, voffA); PG8_SCHED; PG8_LDA(At, 1, 1);
;             PG8_WAIT_V(8); PG8_WAIT_L(0); PG8_BAR; PG8_MMA(1, 0, At, B0); PG8_MMA(1, 1, At, B1); PG8_BAR; PG8_SCHED;
	v_mfma_f32_16x16x32_bf16 v[4:7], v[164:167], v[224:227], v[4:7]
	v_mfma_f32_16x16x32_bf16 v[0:3], v[172:175], v[224:227], v[0:3]
	s_setprio 0
	s_mov_b64 s[98:99], s[30:31]
	s_add_u32 s100, s30, 0x40000
	s_addc_u32 s101, s31, 0
	s_add_i32 s30, 0, 0x18000
	s_add_i32 s31, 0, 0x1c000
	v_add_u32_e32 v144, s30, v183
	v_add_u32_e32 v172, s31, v183
	ds_read_b128 v[132:135], v144
	ds_read_b128 v[136:139], v144 offset:1024
	ds_read_b128 v[140:143], v144 offset:2048
	ds_read_b128 v[144:147], v144 offset:3072
	ds_read_b128 v[148:151], v172
	ds_read_b128 v[164:167], v172 offset:1024
	ds_read_b128 v[168:171], v172 offset:2048
	ds_read_b128 v[172:175], v172 offset:3072
	ds_read_b128 v[176:179], v185 offset:32768
	ds_read_b128 v[186:189], v185 offset:33792
	ds_read_b128 v[204:207], v185 offset:34816
	ds_read_b128 v[208:211], v185 offset:35840
	ds_read_b128 v[212:215], v185 offset:36864
	ds_read_b128 v[216:219], v185 offset:37888
	ds_read_b128 v[220:223], v185 offset:38912
	ds_read_b128 v[224:227], v185 offset:39936
	s_mov_b32 m0, s46
	s_nop 0
	global_load_lds_dwordx4 v152, s[100:101]
	s_mov_b32 m0, s48
	s_nop 0
	global_load_lds_dwordx4 v156, s[100:101]
	s_waitcnt vmcnt(8)
	s_waitcnt lgkmcnt(0)
	s_setprio 2
	s_barrier
	v_mfma_f32_16x16x32_bf16 v[124:127], v[132:135], v[176:179], v[124:127]
	v_mfma_f32_16x16x32_bf16 v[120:123], v[140:143], v[176:179], v[120:123]
	v_mfma_f32_16x16x32_bf16 v[108:111], v[132:135], v[204:207], v[108:111]
	v_mfma_f32_16x16x32_bf16 v[104:107], v[140:143], v[204:207], v[104:107]
	v_mfma_f32_16x16x32_bf16 v[92:95], v[132:135], v[212:215], v[92:95]
	v_mfma_f32_16x16x32_bf16 v[88:91], v[140:143], v[212:215], v[88:91]
	v_mfma_f32_16x16x32_bf16 v[76:79], v[132:135], v[220:223], v[76:79]
	v_mfma_f32_16x16x32_bf16 v[72:75], v[140:143], v[220:223], v[72:75]
	v_mfma_f32_16x16x32_bf16 v[124:127], v[136:139], v[186:189], v[124:127]
	v_mfma_f32_16x16x32_bf16 v[120:123], v[144:147], v[186:189], v[120:123]
	v_mfma_f32_16x16x32_bf16 v[108:111], v[136:139], v[208:211], v[108:111]
	v_mfma_f32_16x16x32_bf16 v[104:107], v[144:147], v[208:211], v[104:107]
	v_mfma_f32_16x16x32_bf16 v[92:95], v[136:139], v[216:219], v[92:95]
	v_mfma_f32_16x16x32_bf16 v[88:91], v[144:147], v[216:219], v[88:91]
	v_mfma_f32_16x16x32_bf16 v[76:79], v[136:139], v[224:227], v[76:79]
	v_mfma_f32_16x16x32_bf16 v[72:75], v[144:147], v[224:227], v[72:75]
	v_mfma_f32_16x16x32_bf16 v[116:119], v[148:151], v[176:179], v[116:119]
	v_mfma_f32_16x16x32_bf16 v[112:115], v[168:171], v[176:179], v[112:115]
	v_mfma_f32_16x16x32_bf16 v[100:103], v[148:151], v[204:207], v[100:103]
	v_mfma_f32_16x16x32_bf16 v[96:99], v[168:171], v[204:207], v[96:99]
	v_mfma_f32_16x16x32_bf16 v[84:87], v[148:151], v[212:215], v[84:87]
	v_mfma_f32_16x16x32_bf16 v[80:83], v[168:171], v[212:215], v[80:83]
	v_mfma_f32_16x16x32_bf16 v[68:71], v[148:151], v[220:223], v[68:71]
	v_mfma_f32_16x16x32_bf16 v[64:67], v[168:171], v[220:223], v[64:67]
	v_mfma_f32_16x16x32_bf16 v[116:119], v[164:167], v[186:189], v[116:119]
	v_mfma_f32_16x16x32_bf16 v[112:115], v[172:175], v[186:189], v[112:115]
	v_mfma_f32_16x16x32_bf16 v[100:103], v[164:167], v[208:211], v[100:103]
	v_mfma_f32_16x16x32_bf16 v[96:99], v[172:175], v[208:211], v[96:99]
	v_mfma_f32_16x16x32_bf16 v[84:87], v[164:167], v[216:219], v[84:87]
	v_mfma_f32_16x16x32_bf16 v[80:83], v[172:175], v[216:219], v[80:83]
	s_setprio 3
	s_barrier
	v_mfma_f32_16x16x32_bf16 v[68:71], v[164:167], v[224:227], v[68:71]
	v_mfma_f32_16x16x32_bf16 v[64:67], v[172:175], v[224:227], v[64:67]
	s_setprio 0
	ds_read_b128 v[176:179], v185 offset:49152
	ds_read_b128 v[186:189], v185 offset:50176
	ds_read_b128 v[204:207], v185 offset:51200
	ds_read_b128 v[208:211], v185 offset:52224
	ds_read_b128 v[212:215], v185 offset:53248
	ds_read_b128 v[216:219], v185 offset:54272
	ds_read_b128 v[220:223], v185 offset:55296
	ds_read_b128 v[224:227], v185 offset:56320
	s_add_u32 s100, s28, 0x80
	s_addc_u32 s101, s29, 0
	s_add_u32 s28, s28, 0x40080
	s_addc_u32 s29, s29, 0
	s_add_u32 s98, s98, 0x80
	s_addc_u32 s99, s99, 0
	s_add_i32 m0, s30, s38
	s_nop 0
	global_load_lds_dwordx4 v154, s[100:101]
	s_add_i32 m0, m0, 0x2000
	s_nop 0
	global_load_lds_dwordx4 v158, s[100:101]
	s_add_i32 m0, s31, s38
	s_nop 0
	global_load_lds_dwordx4 v154, s[28:29]
	s_add_i32 m0, m0, 0x2000
	s_nop 0
	global_load_lds_dwordx4 v158, s[28:29]
	s_mov_b32 m0, s50
	s_nop 0
	global_load_lds_dwordx4 v152, s[98:99]
	s_mov_b32 m0, s51
	s_nop 0
	global_load_lds_dwordx4 v156, s[98:99]
	s_waitcnt vmcnt(8)
	s_waitcnt lgkmcnt(0)
	s_setprio 2
	s_barrier
	v_mfma_f32_16x16x32_bf16 v[60:63], v[132:135], v[176:179], v[60:63]
	v_mfma_f32_16x16x32_bf16 v[56:59], v[140:143], v[176:179], v[56:59]
	v_mfma_f32_16x16x32_bf16 v[44:47], v[132:135], v[204:207], v[44:47]
	v_mfma_f32_16x16x32_bf16 v[40:43], v[140:143], v[204:207], v[40:43]
	v_mfma_f32_16x16x32_bf16 v[28:31], v[132:135], v[212:215], v[28:31]
	v_mfma_f32_16x16x32_bf16 v[24:27], v[140:143], v[212:215], v[24:27]
	v_mfma_f32_16x16x32_bf16 v[12:15], v[132:135], v[220:223], v[12:15]
	v_mfma_f32_16x16x32_bf16 v[8:11], v[140:143], v[220:223], v[8:11]
	v_mfma_f32_16x16x32_bf16 v[60:63], v[136:139], v[186:189], v[60:63]
	v_mfma_f32_16x16x32_bf16 v[56:59], v[144:147], v[186:189], v[56:59]
	v_mfma_f32_16x16x32_bf16 v[44:47], v[136:139], v[208:211], v[44:47]
	v_mfma_f32_16x16x32_bf16 v[40:43], v[144:147], v[208:211], v[40:43]
	v_mfma_f32_16x16x32_bf16 v[28:31], v[136:139], v[216:219], v[28:31]
	v_mfma_f32_16x16x32_bf16 v[24:27], v[144:147], v[216:219], v[24:27]
	v_mfma_f32_16x16x32_bf16 v[12:15], v[136:139], v[224:227], v[12:15]
	v_mfma_f32_16x16x32_bf16 v[8:11], v[144:147], v[224:227], v[8:11]
	v_mfma_f32_16x16x32_bf16 v[52:55], v[148:151], v[176:179], v[52:55]
	v_mfma_f32_16x16x32_bf16 v[48:51], v[168:171], v[176:179], v[48:51]
	v_mfma_f32_16x16x32_bf16 v[36:39], v[148:151], v[204:207], v[36:39]
	v_mfma_f32_16x16x32_bf16 v[32:35], v[168:171], v[204:207], v[32:35]
	v_mfma_f32_16x16x32_bf16 v[20:23], v[148:151], v[212:215], v[20:23]
	v_mfma_f32_16x16x32_bf16 v[16:19], v[168:171], v[212:215], v[16:19]
	v_mfma_f32_16x16x32_bf16 v[4:7], v[148:151], v[220:223], v[4:7]
	v_mfma_f32_16x16x32_bf16 v[0:3], v[168:171], v[220:223], v[0:3]
	v_mfma_f32_16x16x32_bf16 v[52:55], v[164:167], v[186:189], v[52:55]
	v_mfma_f32_16x16x32_bf16 v[48:51], v[172:175], v[186:189], v[48:51]
	v_mfma_f32_16x16x32_bf16 v[36:39], v[164:167], v[208:211], v[36:39]
	v_mfma_f32_16x16x32_bf16 v[32:35], v[172:175], v[208:211], v[32:35]
	v_mfma_f32_16x16x32_bf16 v[20:23], v[164:167], v[216:219], v[20:23]
	v_mfma_f32_16x16x32_bf16 v[16:19], v[172:175], v[216:219], v[16:19]
	s_setprio 3
	s_barrier
	v_mfma_f32_16x16x32_bf16 v[4:7], v[164:167], v[224:227], v[4:7]
	v_mfma_f32_16x16x32_bf16 v[0:3], v[172:175], v[224:227], v[0:3]
	s_setprio 0
	s_add_i32 s58, s58, 2
	s_add_u32 s40, s40, 0x100
	s_addc_u32 s41, s41, 0
	s_cmp_gt_u32 s58, 13
	s_cbranch_scc0 .LBB0_611
	s_and_b64 vcc, exec, s[8:9]
	s_cbranch_vccz .LBB0_614
	s_barrier

; #define PG8_STAGE(bufoff, gbase, voff) do { _Pragma("unroll") for (int _i = 0; _i < 2; ++_i) \
;         __builtin_amdgcn_global_load_lds((const unsigned*)((const char*)(gbase) + (voff)[_i]), (PG8_LAS unsigned*)(lds + (bufoff) + ldsw + _i * 8192), 16, 0, 0); } while (0)
; #define PG8_LDA(dst, b, h) do { _Pragma("unroll") for (int m = 0; m < 4; ++m) _Pragma("unroll") for (int k = 0; k < 2; ++k) dst[m][k] = *(const PG8_LAS bf16x8*)(lds + PG8_SA(b, h) + aoff + m * 2048 + k * 1024); } while (0)
; #define PG8_MMA(ai, bj, At, Bt) do { __builtin_amdgcn_s_setprio(1); _Pragma("unroll") for (int m = 0; m < 4; ++m) _Pragma("unroll") for (int n = 0; n < 2; ++n) _Pragma("unroll") for (int k = 0; k < 2; ++k) \
;         acc[ai][bj][m][n] = __builtin_amdgcn_mfma_f32_16x16x32_bf16(Bt[n][k], At[m][k], acc[ai][bj][m][n], 0, 0, 0); __builtin_amdgcn_s_setprio(0); } while (0)
; #define PG8_WAIT_L(n) asm volatile("s_waitcnt lgkmcnt(" #n ")" ::: "memory")
; #define PG8_WAIT_V8_UNLESS(flag) asm volatile("s_cmp_lg_i32 %0, 0\n\ts_cbranch_scc1 .Lpg8rx%=\n\ts_waitcnt vmcnt(8)\n.Lpg8rx%=:" :: "s"(__builtin_amdgcn_readfirstlane(flag)) : "scc", "memory")
; #define PG8_BAR __builtin_amdgcn_s_barrier()
; #define PG8_SCHED __builtin_amdgcn_sched_barrier(0)
; template <class Epi, class Sched, bool ALIGN_EPI = false, bool SP2 = false>
; __device__ __forceinline__ void gemm_phase(PG8_LAS unsigned char* lds, const Gemm g, const Sched& S, const Epi& E) {
;     ...
;             PG8_WAIT_V8_UNLESS(rx); PG8_WAIT_L(0); PG8_BAR; PG8_MMA(0, 0, At, B0); PG8_MMA(0, 1, At, B1); PG8_BAR; PG8_SCHED;
;             PG8_STAGE(PG8_SB(0, 0), b2, voffB); PG8_STAGE(PG8_SB(0, 1), b2 + hstep, voffB); PG8_STAGE(PG8_SA(0, 0), a2, voffA); PG8_SCHED; PG8_LDA(At, 0, 1);
;             PG8_WAIT_V8_UNLESS(rx); PG8_WAIT_L(0); PG8_BAR; PG8_MMA(1, 0, At, B0); PG8_MMA(1, 1, At, B1); PG8_BAR; PG8_SCHED;
.Lpg8rx6:
	s_waitcnt lgkmcnt(0)
	s_setprio 2
	s_barrier
	v_mfma_f32_16x16x32_bf16 v[152:155], v[120:123], v[164:167], v[152:155]
	v_mfma_f32_16x16x32_bf16 v[148:151], v[132:135], v[164:167], v[148:151]
	v_mfma_f32_16x16x32_bf16 v[108:111], v[120:123], v[172:175], v[108:111]
	v_mfma_f32_16x16x32_bf16 v[104:107], v[132:135], v[172:175], v[104:107]
	v_mfma_f32_16x16x32_bf16 v[92:95], v[120:123], v[180:183], v[92:95]
	v_mfma_f32_16x16x32_bf16 v[88:91], v[132:135], v[180:183], v[88:91]
	v_mfma_f32_16x16x32_bf16 v[76:79], v[120:123], v[188:191], v[76:79]
	v_mfma_f32_16x16x32_bf16 v[72:75], v[132:135], v[188:191], v[72:75]
	v_mfma_f32_16x16x32_bf16 v[152:155], v[128:131], v[168:171], v[152:155]
	v_mfma_f32_16x16x32_bf16 v[148:151], v[136:139], v[168:171], v[148:151]
	v_mfma_f32_16x16x32_bf16 v[108:111], v[128:131], v[176:179], v[108:111]
	v_mfma_f32_16x16x32_bf16 v[104:107], v[136:139], v[176:179], v[104:107]
	v_mfma_f32_16x16x32_bf16 v[92:95], v[128:131], v[184:187], v[92:95]
	v_mfma_f32_16x16x32_bf16 v[88:91], v[136:139], v[184:187], v[88:91]
	v_mfma_f32_16x16x32_bf16 v[76:79], v[128:131], v[214:217], v[76:79]
	v_mfma_f32_16x16x32_bf16 v[72:75], v[136:139], v[214:217], v[72:75]
	v_mfma_f32_16x16x32_bf16 v[124:127], v[140:143], v[164:167], v[124:127]
	v_mfma_f32_16x16x32_bf16 v[112:115], v[156:159], v[164:167], v[112:115]
	v_mfma_f32_16x16x32_bf16 v[100:103], v[140:143], v[172:175], v[100:103]
	v_mfma_f32_16x16x32_bf16 v[96:99], v[156:159], v[172:175], v[96:99]
	v_mfma_f32_16x16x32_bf16 v[84:87], v[140:143], v[180:183], v[84:87]
	v_mfma_f32_16x16x32_bf16 v[80:83], v[156:159], v[180:183], v[80:83]
	v_mfma_f32_16x16x32_bf16 v[68:71], v[140:143], v[188:191], v[68:71]
	v_mfma_f32_16x16x32_bf16 v[64:67], v[156:159], v[188:191], v[64:67]
	v_mfma_f32_16x16x32_bf16 v[124:127], v[144:147], v[168:171], v[124:127]
	v_mfma_f32_16x16x32_bf16 v[112:115], v[160:163], v[168:171], v[112:115]
	v_mfma_f32_16x16x32_bf16 v[100:103], v[144:147], v[176:179], v[100:103]
	v_mfma_f32_16x16x32_bf16 v[96:99], v[160:163], v[176:179], v[96:99]
	v_mfma_f32_16x16x32_bf16 v[84:87], v[144:147], v[184:187], v[84:87]
	v_mfma_f32_16x16x32_bf16 v[80:83], v[160:163], v[184:187], v[80:83]
	s_setprio 3
	s_barrier
	v_mfma_f32_16x16x32_bf16 v[68:71], v[144:147], v[214:217], v[68:71]
	v_mfma_f32_16x16x32_bf16 v[64:67], v[160:163], v[214:217], v[64:67]
	s_setprio 0
	ds_read_b128 v[164:167], v248 offset:16384
	ds_read_b128 v[168:171], v248 offset:17408
	ds_read_b128 v[172:175], v248 offset:18432
	ds_read_b128 v[176:179], v248 offset:19456
	ds_read_b128 v[180:183], v248 offset:20480
	ds_read_b128 v[184:187], v248 offset:21504
	ds_read_b128 v[188:191], v248 offset:22528
	ds_read_b128 v[214:217], v248 offset:23552
	s_add_u32 s58, s28, 0x100000
	s_addc_u32 s59, s29, 0
	s_add_i32 m0, s57, s39
	s_nop 0
	global_load_lds_dwordx4 v194, s[28:29]
	s_add_i32 m0, m0, 0x2000
	s_nop 0
	global_load_lds_dwordx4 v208, s[28:29]
	s_add_i32 m0, s60, s39
	s_nop 0
	global_load_lds_dwordx4 v194, s[58:59]
	s_add_i32 m0, m0, 0x2000
	s_nop 0
	global_load_lds_dwordx4 v208, s[58:59]
	s_mov_b32 m0, s25
	s_nop 0
	global_load_lds_dwordx4 v204, s[30:31]
	s_mov_b32 m0, s42
	s_nop 0
	global_load_lds_dwordx4 v206, s[30:31]
	s_cmp_lg_i32 s61, 0
	s_cbranch_scc1 .Lpg8rx7
	s_waitcnt vmcnt(8)
.Lpg8rx7:
	s_waitcnt lgkmcnt(0)
	s_setprio 2
	s_barrier
	v_mfma_f32_16x16x32_bf16 v[60:63], v[120:123], v[164:167], v[60:63]
	v_mfma_f32_16x16x32_bf16 v[56:59], v[132:135], v[164:167], v[56:59]
	v_mfma_f32_16x16x32_bf16 v[44:47], v[120:123], v[172:175], v[44:47]
	v_mfma_f32_16x16x32_bf16 v[40:43], v[132:135], v[172:175], v[40:43]
	v_mfma_f32_16x16x32_bf16 v[28:31], v[120:123], v[180:183], v[28:31]
	v_mfma_f32_16x16x32_bf16 v[24:27], v[132:135], v[180:183], v[24:27]
	v_mfma_f32_16x16x32_bf16 v[12:15], v[120:123], v[188:191], v[12:15]
	v_mfma_f32_16x16x32_bf16 v[8:11], v[132:135], v[188:191], v[8:11]
	v_mfma_f32_16x16x32_bf16 v[60:63], v[128:131], v[168:171], v[60:63]
	v_mfma_f32_16x16x32_bf16 v[56:59], v[136:139], v[168:171], v[56:59]
	v_mfma_f32_16x16x32_bf16 v[44:47], v[128:131], v[176:179], v[44:47]
	v_mfma_f32_16x16x32_bf16 v[40:43], v[136:139], v[176:179], v[40:43]
	v_mfma_f32_16x16x32_bf16 v[28:31], v[128:131], v[184:187], v[28:31]
	v_mfma_f32_16x16x32_bf16 v[24:27], v[136:139], v[184:187], v[24:27]
	v_mfma_f32_16x16x32_bf16 v[12:15], v[128:131], v[214:217], v[12:15]
	v_mfma_f32_16x16x32_bf16 v[8:11], v[136:139], v[214:217], v[8:11]
	v_mfma_f32_16x16x32_bf16 v[52:55], v[140:143], v[164:167], v[52:55]
	v_mfma_f32_16x16x32_bf16 v[48:51], v[156:159], v[164:167], v[48:51]
	v_mfma_f32_16x16x32_bf16 v[36:39], v[140:143], v[172:175], v[36:39]
	v_mfma_f32_16x16x32_bf16 v[32:35], v[156:159], v[172:175], v[32:35]
	v_mfma_f32_16x16x32_bf16 v[20:23], v[140:143], v[180:183], v[20:23]
	v_mfma_f32_16x16x32_bf16 v[16:19], v[156:159], v[180:183], v[16:19]
	v_mfma_f32_16x16x32_bf16 v[4:7], v[140:143], v[188:191], v[4:7]
	v_mfma_f32_16x16x32_bf16 v[0:3], v[156:159], v[188:191], v[0:3]
	v_mfma_f32_16x16x32_bf16 v[52:55], v[144:147], v[168:171], v[52:55]
	v_mfma_f32_16x16x32_bf16 v[48:51], v[160:163], v[168:171], v[48:51]
	v_mfma_f32_16x16x32_bf16 v[36:39], v[144:147], v[176:179], v[36:39]
	v_mfma_f32_16x16x32_bf16 v[32:35], v[160:163], v[176:179], v[32:35]
	v_mfma_f32_16x16x32_bf16 v[20:23], v[144:147], v[184:187], v[20:23]
	v_mfma_f32_16x16x32_bf16 v[16:19], v[160:163], v[184:187], v[16:19]
	s_setprio 3
	s_barrier
; #define PG8_STAGE(bufoff, gbase, voff) do { _Pragma("unroll") for (int _i = 0; _i < 2; ++_i) \
;         __builtin_amdgcn_global_load_lds((const unsigned*)((const char*)(gbase) + (voff)[_i]), (PG8_LAS unsigned*)(lds + (bufoff) + ldsw + _i * 8192), 16, 0, 0); } while (0)
; #define PG8_LDA(dst, b, h) do { _Pragma("unroll") for (int m = 0; m < 4; ++m) _Pragma("unroll") for (int k = 0; k < 2; ++k) dst[m][k] = *(const PG8_LAS bf16x8*)(lds + PG8_SA(b, h) + aoff + m * 2048 + k * 1024); } while (0)
; #define PG8_LDB(dst, b, h) do { _Pragma("unroll") for (int n = 0; n < 2; ++n) _Pragma("unroll") for (int k = 0; k < 2; ++k) dst[n][k] = *(const PG8_LAS bf16x8*)(lds + PG8_SB(b, h) + boff + n * 2048 + k * 1024); } while (0)
; #define PG8_MMA(ai, bj, At, Bt) do { __builtin_amdgcn_s_setprio(1); _Pragma("unroll") for (int m = 0; m < 4; ++m) _Pragma("unroll") for (int n = 0; n < 2; ++n) _Pragma("unroll") for (int k = 0; k < 2; ++k) \
;         acc[ai][bj][m][n] = __builtin_amdgcn_mfma_f32_16x16x32_bf16(Bt[n][k], At[m][k], acc[ai][bj][m][n], 0, 0, 0); __builtin_amdgcn_s_setprio(0); } while (0)
; #define PG8_WAIT_V(n) asm volatile("s_waitcnt vmcnt(" #n ")" ::: "memory")
; #define PG8_WAIT_L(n) asm volatile("s_waitcnt lgkmcnt(" #n ")" ::: "memory")
; #define PG8_WAIT_V8_UNLESS(flag) asm volatile("s_cmp_lg_i32 %0, 0\n\ts_cbranch_scc1 .Lpg8rx%=\n\ts_waitcnt vmcnt(8)\n.Lpg8rx%=:" :: "s"(__builtin_amdgcn_readfirstlane(flag)) : "scc", "memory")
; #define PG8_BAR __builtin_amdgcn_s_barrier()
; template <class Epi, class Sched, bool ALIGN_EPI = false, bool SP2 = false>
; __device__ __forceinline__ void gemm_phase(PG8_LAS unsigned char* lds, const Gemm g, const Sched& S, const Epi& E) {
;     ...
;             PG8_WAIT_V8_UNLESS(rx); PG8_WAIT_L(0); PG8_BAR; PG8_MMA(1, 0, At, B0); PG8_MMA(1, 1, At, B1); PG8_BAR; PG8_SCHED;
;             PG8_STAGE(PG8_SA(0, 1), a2 + hstep, voffA); PG8_SCHED; PG8_LDB(B0, 1, 0); PG8_LDB(B1, 1, 1); PG8_SCHED; PG8_LDA(At, 1, 0);
;             PG8_WAIT_V(8); PG8_WAIT_L(0); PG8_BAR; PG8_MMA(0, 0, At, B0); PG8_MMA(0, 1, At, B1); PG8_BAR; PG8_SCHED;
;             PG8_STAGE(PG8_SB(1, 0), b3, voffB); PG8_STAGE(PG8_SB(1, 1), b3 + hstep, voffB); PG8_STAGE(PG8_SA(1, 0), a3, voffA); PG8_SCHED; PG8_LDA(At, 1, 1);
;             PG8_WAIT_V(8); PG8_WAIT_L(0); PG8_BAR; PG8_MMA(1, 0, At, B0); PG8_MMA(1, 1, At, B1); PG8_BAR; PG8_SCHED;
	v_mfma_f32_16x16x32_bf16 v[4:7], v[144:147], v[214:217], v[4:7]
	v_mfma_f32_16x16x32_bf16 v[0:3], v[160:163], v[214:217], v[0:3]
	s_setprio 0
	s_mov_b64 s[98:99], s[30:31]
	s_add_u32 s100, s30, 0x100000
	s_addc_u32 s101, s31, 0
	s_add_i32 s30, 0, 0x18000
	s_add_i32 s31, 0, 0x1c000
	v_add_u32_e32 v136, s30, v247
	v_add_u32_e32 v160, s31, v247
	ds_read_b128 v[120:123], v136
	ds_read_b128 v[128:131], v136 offset:1024
	ds_read_b128 v[132:135], v136 offset:2048
	ds_read_b128 v[136:139], v136 offset:3072
	ds_read_b128 v[140:143], v160
	ds_read_b128 v[144:147], v160 offset:1024
	ds_read_b128 v[156:159], v160 offset:2048
	ds_read_b128 v[160:163], v160 offset:3072
	ds_read_b128 v[164:167], v248 offset:32768
	ds_read_b128 v[168:171], v248 offset:33792
	ds_read_b128 v[172:175], v248 offset:34816
	ds_read_b128 v[176:179], v248 offset:35840
	ds_read_b128 v[180:183], v248 offset:36864
	ds_read_b128 v[184:187], v248 offset:37888
	ds_read_b128 v[188:191], v248 offset:38912
	ds_read_b128 v[214:217], v248 offset:39936
	s_mov_b32 m0, s43
	s_nop 0
	global_load_lds_dwordx4 v204, s[100:101]
	s_mov_b32 m0, s44
	s_nop 0
	global_load_lds_dwordx4 v206, s[100:101]
	s_waitcnt vmcnt(8)
	s_waitcnt lgkmcnt(0)
	s_setprio 2
	s_barrier
	v_mfma_f32_16x16x32_bf16 v[152:155], v[120:123], v[164:167], v[152:155]
	v_mfma_f32_16x16x32_bf16 v[148:151], v[132:135], v[164:167], v[148:151]
	v_mfma_f32_16x16x32_bf16 v[108:111], v[120:123], v[172:175], v[108:111]
	v_mfma_f32_16x16x32_bf16 v[104:107], v[132:135], v[172:175], v[104:107]
	v_mfma_f32_16x16x32_bf16 v[92:95], v[120:123], v[180:183], v[92:95]
	v_mfma_f32_16x16x32_bf16 v[88:91], v[132:135], v[180:183], v[88:91]
	v_mfma_f32_16x16x32_bf16 v[76:79], v[120:123], v[188:191], v[76:79]
	v_mfma_f32_16x16x32_bf16 v[72:75], v[132:135], v[188:191], v[72:75]
	v_mfma_f32_16x16x32_bf16 v[152:155], v[128:131], v[168:171], v[152:155]
	v_mfma_f32_16x16x32_bf16 v[148:151], v[136:139], v[168:171], v[148:151]
	v_mfma_f32_16x16x32_bf16 v[108:111], v[128:131], v[176:179], v[108:111]
	v_mfma_f32_16x16x32_bf16 v[104:107], v[136:139], v[176:179], v[104:107]
	v_mfma_f32_16x16x32_bf16 v[92:95], v[128:131], v[184:187], v[92:95]
	v_mfma_f32_16x16x32_bf16 v[88:91], v[136:139], v[184:187], v[88:91]
	v_mfma_f32_16x16x32_bf16 v[76:79], v[128:131], v[214:217], v[76:79]
	v_mfma_f32_16x16x32_bf16 v[72:75], v[136:139], v[214:217], v[72:75]
	v_mfma_f32_16x16x32_bf16 v[124:127], v[140:143], v[164:167], v[124:127]
	v_mfma_f32_16x16x32_bf16 v[112:115], v[156:159], v[164:167], v[112:115]
	v_mfma_f32_16x16x32_bf16 v[100:103], v[140:143], v[172:175], v[100:103]
	v_mfma_f32_16x16x32_bf16 v[96:99], v[156:159], v[172:175], v[96:99]
	v_mfma_f32_16x16x32_bf16 v[84:87], v[140:143], v[180:183], v[84:87]
	v_mfma_f32_16x16x32_bf16 v[80:83], v[156:159], v[180:183], v[80:83]
	v_mfma_f32_16x16x32_bf16 v[68:71], v[140:143], v[188:191], v[68:71]
	v_mfma_f32_16x16x32_bf16 v[64:67], v[156:159], v[188:191], v[64:67]
	v_mfma_f32_16x16x32_bf16 v[124:127], v[144:147], v[168:171], v[124:127]
	v_mfma_f32_16x16x32_bf16 v[112:115], v[160:163], v[168:171], v[112:115]
	v_mfma_f32_16x16x32_bf16 v[100:103], v[144:147], v[176:179], v[100:103]
	v_mfma_f32_16x16x32_bf16 v[96:99], v[160:163], v[176:179], v[96:99]
	v_mfma_f32_16x16x32_bf16 v[84:87], v[144:147], v[184:187], v[84:87]
	v_mfma_f32_16x16x32_bf16 v[80:83], v[160:163], v[184:187], v[80:83]
	s_setprio 3
	s_barrier
	v_mfma_f32_16x16x32_bf16 v[68:71], v[144:147], v[214:217], v[68:71]
	v_mfma_f32_16x16x32_bf16 v[64:67], v[160:163], v[214:217], v[64:67]
	s_setprio 0
	ds_read_b128 v[164:167], v248 offset:49152
	ds_read_b128 v[168:171], v248 offset:50176
	ds_read_b128 v[172:175], v248 offset:51200
	ds_read_b128 v[176:179], v248 offset:52224
	ds_read_b128 v[180:183], v248 offset:53248
	ds_read_b128 v[184:187], v248 offset:54272
	ds_read_b128 v[188:191], v248 offset:55296
	ds_read_b128 v[214:217], v248 offset:56320
	s_add_u32 s100, s28, 0x80
	s_addc_u32 s101, s29, 0
	s_add_u32 s28, s28, 0x100080
	s_addc_u32 s29, s29, 0
	s_add_u32 s98, s98, 0x80
	s_addc_u32 s99, s99, 0
	s_add_i32 m0, s30, s39
	s_nop 0
	global_load_lds_dwordx4 v194, s[100:101]
	s_add_i32 m0, m0, 0x2000
	s_nop 0
	global_load_lds_dwordx4 v208, s[100:101]
	s_add_i32 m0, s31, s39
	s_nop 0
	global_load_lds_dwordx4 v194, s[28:29]
	s_add_i32 m0, m0, 0x2000
	s_nop 0
	global_load_lds_dwordx4 v208, s[28:29]
	s_mov_b32 m0, s46
	s_nop 0
	global_load_lds_dwordx4 v204, s[98:99]
	s_mov_b32 m0, s48
	s_nop 0
	global_load_lds_dwordx4 v206, s[98:99]
	s_waitcnt vmcnt(8)
	s_waitcnt lgkmcnt(0)
	s_setprio 2
	s_barrier
	v_mfma_f32_16x16x32_bf16 v[60:63], v[120:123], v[164:167], v[60:63]
	v_mfma_f32_16x16x32_bf16 v[56:59], v[132:135], v[164:167], v[56:59]
	v_mfma_f32_16x16x32_bf16 v[44:47], v[120:123], v[172:175], v[44:47]
	v_mfma_f32_16x16x32_bf16 v[40:43], v[132:135], v[172:175], v[40:43]
	v_mfma_f32_16x16x32_bf16 v[28:31], v[120:123], v[180:183], v[28:31]
	v_mfma_f32_16x16x32_bf16 v[24:27], v[132:135], v[180:183], v[24:27]
	v_mfma_f32_16x16x32_bf16 v[12:15], v[120:123], v[188:191], v[12:15]
	v_mfma_f32_16x16x32_bf16 v[8:11], v[132:135], v[188:191], v[8:11]
	v_mfma_f32_16x16x32_bf16 v[60:63], v[128:131], v[168:171], v[60:63]
	v_mfma_f32_16x16x32_bf16 v[56:59], v[136:139], v[168:171], v[56:59]
	v_mfma_f32_16x16x32_bf16 v[44:47], v[128:131], v[176:179], v[44:47]
	v_mfma_f32_16x16x32_bf16 v[40:43], v[136:139], v[176:179], v[40:43]
	v_mfma_f32_16x16x32_bf16 v[28:31], v[128:131], v[184:187], v[28:31]
	v_mfma_f32_16x16x32_bf16 v[24:27], v[136:139], v[184:187], v[24:27]
	v_mfma_f32_16x16x32_bf16 v[12:15], v[128:131], v[214:217], v[12:15]
	v_mfma_f32_16x16x32_bf16 v[8:11], v[136:139], v[214:217], v[8:11]
	v_mfma_f32_16x16x32_bf16 v[52:55], v[140:143], v[164:167], v[52:55]
	v_mfma_f32_16x16x32_bf16 v[48:51], v[156:159], v[164:167], v[48:51]
	v_mfma_f32_16x16x32_bf16 v[36:39], v[140:143], v[172:175], v[36:39]
	v_mfma_f32_16x16x32_bf16 v[32:35], v[156:159], v[172:175], v[32:35]
	v_mfma_f32_16x16x32_bf16 v[20:23], v[140:143], v[180:183], v[20:23]
	v_mfma_f32_16x16x32_bf16 v[16:19], v[156:159], v[180:183], v[16:19]
	v_mfma_f32_16x16x32_bf16 v[4:7], v[140:143], v[188:191], v[4:7]
	v_mfma_f32_16x16x32_bf16 v[0:3], v[156:159], v[188:191], v[0:3]
	v_mfma_f32_16x16x32_bf16 v[52:55], v[144:147], v[168:171], v[52:55]
	v_mfma_f32_16x16x32_bf16 v[48:51], v[160:163], v[168:171], v[48:51]
	v_mfma_f32_16x16x32_bf16 v[36:39], v[144:147], v[176:179], v[36:39]
	v_mfma_f32_16x16x32_bf16 v[32:35], v[160:163], v[176:179], v[32:35]
	v_mfma_f32_16x16x32_bf16 v[20:23], v[144:147], v[184:187], v[20:23]
	v_mfma_f32_16x16x32_bf16 v[16:19], v[160:163], v[184:187], v[16:19]
	s_setprio 3
	s_barrier
	v_mfma_f32_16x16x32_bf16 v[4:7], v[144:147], v[214:217], v[4:7]
	v_mfma_f32_16x16x32_bf16 v[0:3], v[160:163], v[214:217], v[0:3]
	s_setprio 0
	s_add_i32 s56, s56, 2
	s_add_u32 s40, s40, 0x100
	s_addc_u32 s41, s41, 0
	s_cmp_gt_u32 s56, 61
	s_cbranch_scc0 .LBB0_965
	s_and_b64 vcc, exec, s[10:11]
	s_cbranch_vccz .LBB0_968
	s_barrier

; #define PG8_STAGE(bufoff, gbase, voff) do { _Pragma("unroll") for (int _i = 0; _i < 2; ++_i) \
;         __builtin_amdgcn_global_load_lds((const unsigned*)((const char*)(gbase) + (voff)[_i]), (PG8_LAS unsigned*)(lds + (bufoff) + ldsw + _i * 8192), 16, 0, 0); } while (0)
; #define PG8_LDA(dst, b, h) do { _Pragma("unroll") for (int m = 0; m < 4; ++m) _Pragma("unroll") for (int k = 0; k < 2; ++k) dst[m][k] = *(const PG8_LAS bf16x8*)(lds + PG8_SA(b, h) + aoff + m * 2048 + k * 1024); } while (0)
; #define PG8_MMA(ai, bj, At, Bt) do { __builtin_amdgcn_s_setprio(1); _Pragma("unroll") for (int m = 0; m < 4; ++m) _Pragma("unroll") for (int n = 0; n < 2; ++n) _Pragma("unroll") for (int k = 0; k < 2; ++k) \
;         acc[ai][bj][m][n] = __builtin_amdgcn_mfma_f32_16x16x32_bf16(Bt[n][k], At[m][k], acc[ai][bj][m][n], 0, 0, 0); __builtin_amdgcn_s_setprio(0); } while (0)
; #define PG8_WAIT_L(n) asm volatile("s_waitcnt lgkmcnt(" #n ")" ::: "memory")
; #define PG8_WAIT_V8_UNLESS(flag) asm volatile("s_cmp_lg_i32 %0, 0\n\ts_cbranch_scc1 .Lpg8rx%=\n\ts_waitcnt vmcnt(8)\n.Lpg8rx%=:" :: "s"(__builtin_amdgcn_readfirstlane(flag)) : "scc", "memory")
; #define PG8_BAR __builtin_amdgcn_s_barrier()
; #define PG8_SCHED __builtin_amdgcn_sched_barrier(0)
; template <class Epi, class Sched, bool ALIGN_EPI = false, bool SP2 = false>
; __device__ __forceinline__ void gemm_phase(PG8_LAS unsigned char* lds, const Gemm g, const Sched& S, const Epi& E) {
;     ...
;             PG8_WAIT_V8_UNLESS(rx); PG8_WAIT_L(0); PG8_BAR; PG8_MMA(0, 0, At, B0); PG8_MMA(0, 1, At, B1); PG8_BAR; PG8_SCHED;
;             PG8_STAGE(PG8_SB(0, 0), b2, voffB); PG8_STAGE(PG8_SB(0, 1), b2 + hstep, voffB); PG8_STAGE(PG8_SA(0, 0), a2, voffA); PG8_SCHED; PG8_LDA(At, 0, 1);
;             PG8_WAIT_V8_UNLESS(rx); PG8_WAIT_L(0); PG8_BAR; PG8_MMA(1, 0, At, B0); PG8_MMA(1, 1, At, B1); PG8_BAR; PG8_SCHED;
.Lpg8rx8:
	s_waitcnt lgkmcnt(0)
	s_setprio 2
	s_barrier
	v_mfma_f32_16x16x32_bf16 v[120:123], v[140:143], v[172:175], v[120:123]
	v_mfma_f32_16x16x32_bf16 v[124:127], v[148:151], v[172:175], v[124:127]
	v_mfma_f32_16x16x32_bf16 v[108:111], v[140:143], v[180:183], v[108:111]
	v_mfma_f32_16x16x32_bf16 v[104:107], v[148:151], v[180:183], v[104:107]
	v_mfma_f32_16x16x32_bf16 v[92:95], v[140:143], v[188:191], v[92:95]
	v_mfma_f32_16x16x32_bf16 v[88:91], v[148:151], v[188:191], v[88:91]
	v_mfma_f32_16x16x32_bf16 v[76:79], v[140:143], v[208:211], v[76:79]
	v_mfma_f32_16x16x32_bf16 v[72:75], v[148:151], v[208:211], v[72:75]
	v_mfma_f32_16x16x32_bf16 v[120:123], v[144:147], v[176:179], v[120:123]
	v_mfma_f32_16x16x32_bf16 v[124:127], v[152:155], v[176:179], v[124:127]
	v_mfma_f32_16x16x32_bf16 v[108:111], v[144:147], v[184:187], v[108:111]
	v_mfma_f32_16x16x32_bf16 v[104:107], v[152:155], v[184:187], v[104:107]
	v_mfma_f32_16x16x32_bf16 v[92:95], v[144:147], v[204:207], v[92:95]
	v_mfma_f32_16x16x32_bf16 v[88:91], v[152:155], v[204:207], v[88:91]
	v_mfma_f32_16x16x32_bf16 v[76:79], v[144:147], v[212:215], v[76:79]
	v_mfma_f32_16x16x32_bf16 v[72:75], v[152:155], v[212:215], v[72:75]
	v_mfma_f32_16x16x32_bf16 v[116:119], v[156:159], v[172:175], v[116:119]
	v_mfma_f32_16x16x32_bf16 v[112:115], v[164:167], v[172:175], v[112:115]
	v_mfma_f32_16x16x32_bf16 v[100:103], v[156:159], v[180:183], v[100:103]
	v_mfma_f32_16x16x32_bf16 v[96:99], v[164:167], v[180:183], v[96:99]
	v_mfma_f32_16x16x32_bf16 v[84:87], v[156:159], v[188:191], v[84:87]
	v_mfma_f32_16x16x32_bf16 v[80:83], v[164:167], v[188:191], v[80:83]
	v_mfma_f32_16x16x32_bf16 v[68:71], v[156:159], v[208:211], v[68:71]
	v_mfma_f32_16x16x32_bf16 v[64:67], v[164:167], v[208:211], v[64:67]
	v_mfma_f32_16x16x32_bf16 v[116:119], v[160:163], v[176:179], v[116:119]
	v_mfma_f32_16x16x32_bf16 v[112:115], v[168:171], v[176:179], v[112:115]
	v_mfma_f32_16x16x32_bf16 v[100:103], v[160:163], v[184:187], v[100:103]
	v_mfma_f32_16x16x32_bf16 v[96:99], v[168:171], v[184:187], v[96:99]
	v_mfma_f32_16x16x32_bf16 v[84:87], v[160:163], v[204:207], v[84:87]
	v_mfma_f32_16x16x32_bf16 v[80:83], v[168:171], v[204:207], v[80:83]
	s_setprio 3
	s_barrier
	v_mfma_f32_16x16x32_bf16 v[68:71], v[160:163], v[212:215], v[68:71]
	v_mfma_f32_16x16x32_bf16 v[64:67], v[168:171], v[212:215], v[64:67]
	s_setprio 0
	s_add_i32 s63, s63, s34
	v_lshl_add_u64 v[216:217], s[66:67], 0, v[194:195]
	s_mov_b32 m0, s63
	v_lshl_add_u64 v[218:219], s[66:67], 0, v[132:133]
	global_load_lds_dwordx4 v[216:217], off
	s_add_i32 m0, s63, 0x2000
	s_add_u32 s66, s66, s8
	s_addc_u32 s67, s67, s9
	s_add_i32 s63, s65, s34
	global_load_lds_dwordx4 v[218:219], off
	v_lshl_add_u64 v[220:221], s[66:67], 0, v[194:195]
	s_mov_b32 m0, s63
	v_lshl_add_u64 v[222:223], s[66:67], 0, v[132:133]
	global_load_lds_dwordx4 v[220:221], off
	s_add_i32 m0, s63, 0x2000
	v_lshl_add_u64 v[224:225], s[24:25], 0, v[128:129]
	global_load_lds_dwordx4 v[222:223], off
	s_mov_b32 m0, s43
	v_lshl_add_u64 v[226:227], s[24:25], 0, v[130:131]
	global_load_lds_dwordx4 v[224:225], off
	s_mov_b32 m0, s44
	s_nop 0
	global_load_lds_dwordx4 v[226:227], off
	ds_read_b128 v[172:175], v139 offset:16384
	ds_read_b128 v[176:179], v139 offset:17408
	ds_read_b128 v[180:183], v139 offset:18432
	ds_read_b128 v[184:187], v139 offset:19456
	ds_read_b128 v[188:191], v139 offset:20480
	ds_read_b128 v[204:207], v139 offset:21504
	ds_read_b128 v[208:211], v139 offset:22528
	ds_read_b128 v[212:215], v139 offset:23552
	s_cmp_lg_i32 s73, 0
	s_cbranch_scc1 .Lpg8rx9
	s_waitcnt vmcnt(8)
.Lpg8rx9:
	s_waitcnt lgkmcnt(0)
	s_setprio 2
	s_barrier
	v_mfma_f32_16x16x32_bf16 v[60:63], v[140:143], v[172:175], v[60:63]
	v_mfma_f32_16x16x32_bf16 v[56:59], v[148:151], v[172:175], v[56:59]
	v_mfma_f32_16x16x32_bf16 v[44:47], v[140:143], v[180:183], v[44:47]
	v_mfma_f32_16x16x32_bf16 v[40:43], v[148:151], v[180:183], v[40:43]
	v_mfma_f32_16x16x32_bf16 v[28:31], v[140:143], v[188:191], v[28:31]
	v_mfma_f32_16x16x32_bf16 v[24:27], v[148:151], v[188:191], v[24:27]
	v_mfma_f32_16x16x32_bf16 v[12:15], v[140:143], v[208:211], v[12:15]
	v_mfma_f32_16x16x32_bf16 v[8:11], v[148:151], v[208:211], v[8:11]
	v_mfma_f32_16x16x32_bf16 v[60:63], v[144:147], v[176:179], v[60:63]
	v_mfma_f32_16x16x32_bf16 v[56:59], v[152:155], v[176:179], v[56:59]
	v_mfma_f32_16x16x32_bf16 v[44:47], v[144:147], v[184:187], v[44:47]
	v_mfma_f32_16x16x32_bf16 v[40:43], v[152:155], v[184:187], v[40:43]
	v_mfma_f32_16x16x32_bf16 v[28:31], v[144:147], v[204:207], v[28:31]
	v_mfma_f32_16x16x32_bf16 v[24:27], v[152:155], v[204:207], v[24:27]
	v_mfma_f32_16x16x32_bf16 v[12:15], v[144:147], v[212:215], v[12:15]
	v_mfma_f32_16x16x32_bf16 v[8:11], v[152:155], v[212:215], v[8:11]
	v_mfma_f32_16x16x32_bf16 v[52:55], v[156:159], v[172:175], v[52:55]
	v_mfma_f32_16x16x32_bf16 v[48:51], v[164:167], v[172:175], v[48:51]
	v_mfma_f32_16x16x32_bf16 v[36:39], v[156:159], v[180:183], v[36:39]
	v_mfma_f32_16x16x32_bf16 v[32:35], v[164:167], v[180:183], v[32:35]
	v_mfma_f32_16x16x32_bf16 v[20:23], v[156:159], v[188:191], v[20:23]
	v_mfma_f32_16x16x32_bf16 v[16:19], v[164:167], v[188:191], v[16:19]
	v_mfma_f32_16x16x32_bf16 v[4:7], v[156:159], v[208:211], v[4:7]
	v_mfma_f32_16x16x32_bf16 v[0:3], v[164:167], v[208:211], v[0:3]
	v_mfma_f32_16x16x32_bf16 v[52:55], v[160:163], v[176:179], v[52:55]
	v_mfma_f32_16x16x32_bf16 v[48:51], v[168:171], v[176:179], v[48:51]
	v_mfma_f32_16x16x32_bf16 v[36:39], v[160:163], v[184:187], v[36:39]
	v_mfma_f32_16x16x32_bf16 v[32:35], v[168:171], v[184:187], v[32:35]
	v_mfma_f32_16x16x32_bf16 v[20:23], v[160:163], v[204:207], v[20:23]
	v_mfma_f32_16x16x32_bf16 v[16:19], v[168:171], v[204:207], v[16:19]
	s_setprio 3
	s_barrier
; #define PG8_STAGE(bufoff, gbase, voff) do { _Pragma("unroll") for (int _i = 0; _i < 2; ++_i) \
;         __builtin_amdgcn_global_load_lds((const unsigned*)((const char*)(gbase) + (voff)[_i]), (PG8_LAS unsigned*)(lds + (bufoff) + ldsw + _i * 8192), 16, 0, 0); } while (0)
; #define PG8_LDA(dst, b, h) do { _Pragma("unroll") for (int m = 0; m < 4; ++m) _Pragma("unroll") for (int k = 0; k < 2; ++k) dst[m][k] = *(const PG8_LAS bf16x8*)(lds + PG8_SA(b, h) + aoff + m * 2048 + k * 1024); } while (0)
; #define PG8_LDB(dst, b, h) do { _Pragma("unroll") for (int n = 0; n < 2; ++n) _Pragma("unroll") for (int k = 0; k < 2; ++k) dst[n][k] = *(const PG8_LAS bf16x8*)(lds + PG8_SB(b, h) + boff + n * 2048 + k * 1024); } while (0)
; #define PG8_MMA(ai, bj, At, Bt) do { __builtin_amdgcn_s_setprio(1); _Pragma("unroll") for (int m = 0; m < 4; ++m) _Pragma("unroll") for (int n = 0; n < 2; ++n) _Pragma("unroll") for (int k = 0; k < 2; ++k) \
;         acc[ai][bj][m][n] = __builtin_amdgcn_mfma_f32_16x16x32_bf16(Bt[n][k], At[m][k], acc[ai][bj][m][n], 0, 0, 0); __builtin_amdgcn_s_setprio(0); } while (0)
; #define PG8_WAIT_V(n) asm volatile("s_waitcnt vmcnt(" #n ")" ::: "memory")
; #define PG8_WAIT_L(n) asm volatile("s_waitcnt lgkmcnt(" #n ")" ::: "memory")
; #define PG8_WAIT_V8_UNLESS(flag) asm volatile("s_cmp_lg_i32 %0, 0\n\ts_cbranch_scc1 .Lpg8rx%=\n\ts_waitcnt vmcnt(8)\n.Lpg8rx%=:" :: "s"(__builtin_amdgcn_readfirstlane(flag)) : "scc", "memory")
; #define PG8_BAR __builtin_amdgcn_s_barrier()
; #define PG8_SCHED __builtin_amdgcn_sched_barrier(0)
; template <class Epi, class Sched, bool ALIGN_EPI = false, bool SP2 = false>
; __device__ __forceinline__ void gemm_phase(PG8_LAS unsigned char* lds, const Gemm g, const Sched& S, const Epi& E) {
;     ...
;             PG8_WAIT_V8_UNLESS(rx); PG8_WAIT_L(0); PG8_BAR; PG8_MMA(1, 0, At, B0); PG8_MMA(1, 1, At, B1); PG8_BAR; PG8_SCHED;
;             PG8_STAGE(PG8_SA(0, 1), a2 + hstep, voffA); PG8_SCHED; PG8_LDB(B0, 1, 0); PG8_LDB(B1, 1, 1); PG8_SCHED; PG8_LDA(At, 1, 0);
;             PG8_WAIT_V(8); PG8_WAIT_L(0); PG8_BAR; PG8_MMA(0, 0, At, B0); PG8_MMA(0, 1, At, B1); PG8_BAR; PG8_SCHED;
	v_mfma_f32_16x16x32_bf16 v[4:7], v[160:163], v[212:215], v[4:7]
	v_mfma_f32_16x16x32_bf16 v[0:3], v[168:171], v[212:215], v[0:3]
	s_setprio 0
	s_add_u32 s24, s24, s8
	s_addc_u32 s25, s25, s9
	s_mov_b32 m0, s46
	v_lshl_add_u64 v[140:141], s[24:25], 0, v[128:129]
	global_load_lds_dwordx4 v[140:141], off
	v_lshl_add_u64 v[140:141], s[24:25], 0, v[130:131]
	s_mov_b32 m0, s48
	s_nop 0
	global_load_lds_dwordx4 v[140:141], off
	s_add_i32 s24, 0, 0x18000
	s_add_i32 s25, 0, 0x1c000
	v_add_u32_e32 v152, s24, v138
	v_add_u32_e32 v168, s25, v138
	ds_read_b128 v[140:143], v152
	ds_read_b128 v[144:147], v152 offset:1024
	ds_read_b128 v[148:151], v152 offset:2048
	ds_read_b128 v[152:155], v152 offset:3072
	ds_read_b128 v[156:159], v168
	ds_read_b128 v[160:163], v168 offset:1024
	ds_read_b128 v[164:167], v168 offset:2048
	ds_read_b128 v[168:171], v168 offset:3072
	ds_read_b128 v[172:175], v139 offset:32768
	ds_read_b128 v[176:179], v139 offset:33792
	ds_read_b128 v[180:183], v139 offset:34816
	ds_read_b128 v[184:187], v139 offset:35840
	ds_read_b128 v[188:191], v139 offset:36864
	ds_read_b128 v[204:207], v139 offset:37888
	ds_read_b128 v[208:211], v139 offset:38912
	ds_read_b128 v[212:215], v139 offset:39936
	s_waitcnt vmcnt(8)
	s_waitcnt lgkmcnt(0)
	s_setprio 2
	s_barrier
	v_mfma_f32_16x16x32_bf16 v[120:123], v[140:143], v[172:175], v[120:123]
	v_mfma_f32_16x16x32_bf16 v[124:127], v[148:151], v[172:175], v[124:127]
	v_mfma_f32_16x16x32_bf16 v[108:111], v[140:143], v[180:183], v[108:111]
	v_mfma_f32_16x16x32_bf16 v[104:107], v[148:151], v[180:183], v[104:107]
	v_mfma_f32_16x16x32_bf16 v[92:95], v[140:143], v[188:191], v[92:95]
	v_mfma_f32_16x16x32_bf16 v[88:91], v[148:151], v[188:191], v[88:91]
	v_mfma_f32_16x16x32_bf16 v[76:79], v[140:143], v[208:211], v[76:79]
	v_mfma_f32_16x16x32_bf16 v[72:75], v[148:151], v[208:211], v[72:75]
	v_mfma_f32_16x16x32_bf16 v[120:123], v[144:147], v[176:179], v[120:123]
	v_mfma_f32_16x16x32_bf16 v[124:127], v[152:155], v[176:179], v[124:127]
	v_mfma_f32_16x16x32_bf16 v[108:111], v[144:147], v[184:187], v[108:111]
	v_mfma_f32_16x16x32_bf16 v[104:107], v[152:155], v[184:187], v[104:107]
	v_mfma_f32_16x16x32_bf16 v[92:95], v[144:147], v[204:207], v[92:95]
	v_mfma_f32_16x16x32_bf16 v[88:91], v[152:155], v[204:207], v[88:91]
	v_mfma_f32_16x16x32_bf16 v[76:79], v[144:147], v[212:215], v[76:79]
	v_mfma_f32_16x16x32_bf16 v[72:75], v[152:155], v[212:215], v[72:75]
	v_mfma_f32_16x16x32_bf16 v[116:119], v[156:159], v[172:175], v[116:119]
	v_mfma_f32_16x16x32_bf16 v[112:115], v[164:167], v[172:175], v[112:115]
	v_mfma_f32_16x16x32_bf16 v[100:103], v[156:159], v[180:183], v[100:103]
	v_mfma_f32_16x16x32_bf16 v[96:99], v[164:167], v[180:183], v[96:99]
	v_mfma_f32_16x16x32_bf16 v[84:87], v[156:159], v[188:191], v[84:87]
	v_mfma_f32_16x16x32_bf16 v[80:83], v[164:167], v[188:191], v[80:83]
	v_mfma_f32_16x16x32_bf16 v[68:71], v[156:159], v[208:211], v[68:71]
	v_mfma_f32_16x16x32_bf16 v[64:67], v[164:167], v[208:211], v[64:67]
	v_mfma_f32_16x16x32_bf16 v[116:119], v[160:163], v[176:179], v[116:119]
	v_mfma_f32_16x16x32_bf16 v[112:115], v[168:171], v[176:179], v[112:115]
	v_mfma_f32_16x16x32_bf16 v[100:103], v[160:163], v[184:187], v[100:103]
	v_mfma_f32_16x16x32_bf16 v[96:99], v[168:171], v[184:187], v[96:99]
	v_mfma_f32_16x16x32_bf16 v[84:87], v[160:163], v[204:207], v[84:87]
	v_mfma_f32_16x16x32_bf16 v[80:83], v[168:171], v[204:207], v[80:83]
	s_setprio 3
	s_barrier
; #define PG8_STAGE(bufoff, gbase, voff) do { _Pragma("unroll") for (int _i = 0; _i < 2; ++_i) \
;         __builtin_amdgcn_global_load_lds((const unsigned*)((const char*)(gbase) + (voff)[_i]), (PG8_LAS unsigned*)(lds + (bufoff) + ldsw + _i * 8192), 16, 0, 0); } while (0)
; #define PG8_LDA(dst, b, h) do { _Pragma("unroll") for (int m = 0; m < 4; ++m) _Pragma("unroll") for (int k = 0; k < 2; ++k) dst[m][k] = *(const PG8_LAS bf16x8*)(lds + PG8_SA(b, h) + aoff + m * 2048 + k * 1024); } while (0)
; #define PG8_MMA(ai, bj, At, Bt) do { __builtin_amdgcn_s_setprio(1); _Pragma("unroll") for (int m = 0; m < 4; ++m) _Pragma("unroll") for (int n = 0; n < 2; ++n) _Pragma("unroll") for (int k = 0; k < 2; ++k) \
;         acc[ai][bj][m][n] = __builtin_amdgcn_mfma_f32_16x16x32_bf16(Bt[n][k], At[m][k], acc[ai][bj][m][n], 0, 0, 0); __builtin_amdgcn_s_setprio(0); } while (0)
; #define PG8_WAIT_V(n) asm volatile("s_waitcnt vmcnt(" #n ")" ::: "memory")
; #define PG8_WAIT_L(n) asm volatile("s_waitcnt lgkmcnt(" #n ")" ::: "memory")
; #define PG8_BAR __builtin_amdgcn_s_barrier()
; #define PG8_SCHED __builtin_amdgcn_sched_barrier(0)
; template <class Epi, class Sched, bool ALIGN_EPI = false, bool SP2 = false>
; __device__ __forceinline__ void gemm_phase(PG8_LAS unsigned char* lds, const Gemm g, const Sched& S, const Epi& E) {
;     ...
;             PG8_WAIT_V(8); PG8_WAIT_L(0); PG8_BAR; PG8_MMA(0, 0, At, B0); PG8_MMA(0, 1, At, B1); PG8_BAR; PG8_SCHED;
;             PG8_STAGE(PG8_SB(1, 0), b3, voffB); PG8_STAGE(PG8_SB(1, 1), b3 + hstep, voffB); PG8_STAGE(PG8_SA(1, 0), a3, voffA); PG8_SCHED; PG8_LDA(At, 1, 1);
;             PG8_WAIT_V(8); PG8_WAIT_L(0); PG8_BAR; PG8_MMA(1, 0, At, B0); PG8_MMA(1, 1, At, B1); PG8_BAR; PG8_SCHED;
	v_mfma_f32_16x16x32_bf16 v[68:71], v[160:163], v[212:215], v[68:71]
	v_mfma_f32_16x16x32_bf16 v[64:67], v[168:171], v[212:215], v[64:67]
	s_setprio 0
	s_add_i32 s24, s24, s34
	v_lshl_add_u64 v[172:173], v[216:217], 0, s[74:75]
	s_mov_b32 m0, s24
	s_nop 0
	global_load_lds_dwordx4 v[172:173], off
	v_lshl_add_u64 v[172:173], v[218:219], 0, s[74:75]
	s_add_i32 m0, s24, 0x2000
	s_add_i32 s24, s25, s34
	global_load_lds_dwordx4 v[172:173], off
	v_lshl_add_u64 v[172:173], v[220:221], 0, s[74:75]
	s_mov_b32 m0, s24
	s_nop 0
	global_load_lds_dwordx4 v[172:173], off
	v_lshl_add_u64 v[172:173], v[222:223], 0, s[74:75]
	s_add_i32 m0, s24, 0x2000
	s_nop 0
	global_load_lds_dwordx4 v[172:173], off
	v_lshl_add_u64 v[172:173], v[224:225], 0, s[74:75]
	s_mov_b32 m0, s53
	s_nop 0
	global_load_lds_dwordx4 v[172:173], off
	v_lshl_add_u64 v[172:173], v[226:227], 0, s[74:75]
	s_mov_b32 m0, s54
	s_nop 0
	global_load_lds_dwordx4 v[172:173], off
	ds_read_b128 v[172:175], v139 offset:49152
	ds_read_b128 v[176:179], v139 offset:50176
	ds_read_b128 v[180:183], v139 offset:51200
	ds_read_b128 v[184:187], v139 offset:52224
	ds_read_b128 v[188:191], v139 offset:53248
	ds_read_b128 v[204:207], v139 offset:54272
	ds_read_b128 v[208:211], v139 offset:55296
	ds_read_b128 v[212:215], v139 offset:56320
	s_waitcnt vmcnt(8)
	s_waitcnt lgkmcnt(0)
	s_setprio 2
	s_barrier
	v_mfma_f32_16x16x32_bf16 v[60:63], v[140:143], v[172:175], v[60:63]
	v_mfma_f32_16x16x32_bf16 v[56:59], v[148:151], v[172:175], v[56:59]
	v_mfma_f32_16x16x32_bf16 v[44:47], v[140:143], v[180:183], v[44:47]
	v_mfma_f32_16x16x32_bf16 v[40:43], v[148:151], v[180:183], v[40:43]
	v_mfma_f32_16x16x32_bf16 v[28:31], v[140:143], v[188:191], v[28:31]
	v_mfma_f32_16x16x32_bf16 v[24:27], v[148:151], v[188:191], v[24:27]
	v_mfma_f32_16x16x32_bf16 v[12:15], v[140:143], v[208:211], v[12:15]
	v_mfma_f32_16x16x32_bf16 v[8:11], v[148:151], v[208:211], v[8:11]
	v_mfma_f32_16x16x32_bf16 v[60:63], v[144:147], v[176:179], v[60:63]
	v_mfma_f32_16x16x32_bf16 v[56:59], v[152:155], v[176:179], v[56:59]
	v_mfma_f32_16x16x32_bf16 v[44:47], v[144:147], v[184:187], v[44:47]
	v_mfma_f32_16x16x32_bf16 v[40:43], v[152:155], v[184:187], v[40:43]
	v_mfma_f32_16x16x32_bf16 v[28:31], v[144:147], v[204:207], v[28:31]
	v_mfma_f32_16x16x32_bf16 v[24:27], v[152:155], v[204:207], v[24:27]
	v_mfma_f32_16x16x32_bf16 v[12:15], v[144:147], v[212:215], v[12:15]
	v_mfma_f32_16x16x32_bf16 v[8:11], v[152:155], v[212:215], v[8:11]
	v_mfma_f32_16x16x32_bf16 v[52:55], v[156:159], v[172:175], v[52:55]
	v_mfma_f32_16x16x32_bf16 v[48:51], v[164:167], v[172:175], v[48:51]
	v_mfma_f32_16x16x32_bf16 v[36:39], v[156:159], v[180:183], v[36:39]
	v_mfma_f32_16x16x32_bf16 v[32:35], v[164:167], v[180:183], v[32:35]
	v_mfma_f32_16x16x32_bf16 v[20:23], v[156:159], v[188:191], v[20:23]
	v_mfma_f32_16x16x32_bf16 v[16:19], v[164:167], v[188:191], v[16:19]
	v_mfma_f32_16x16x32_bf16 v[4:7], v[156:159], v[208:211], v[4:7]
	v_mfma_f32_16x16x32_bf16 v[0:3], v[164:167], v[208:211], v[0:3]
	v_mfma_f32_16x16x32_bf16 v[52:55], v[160:163], v[176:179], v[52:55]
	v_mfma_f32_16x16x32_bf16 v[48:51], v[168:171], v[176:179], v[48:51]
	v_mfma_f32_16x16x32_bf16 v[36:39], v[160:163], v[184:187], v[36:39]
	v_mfma_f32_16x16x32_bf16 v[32:35], v[168:171], v[184:187], v[32:35]
	v_mfma_f32_16x16x32_bf16 v[20:23], v[160:163], v[204:207], v[20:23]
	v_mfma_f32_16x16x32_bf16 v[16:19], v[168:171], v[204:207], v[16:19]
	s_setprio 3
	s_barrier
	v_mfma_f32_16x16x32_bf16 v[4:7], v[160:163], v[212:215], v[4:7]
	v_mfma_f32_16x16x32_bf16 v[0:3], v[168:171], v[212:215], v[0:3]
	s_setprio 0
	s_add_u32 s22, s22, 0x100
	s_addc_u32 s23, s23, 0
	s_add_u32 s60, s60, 0x100
	s_addc_u32 s61, s61, 0
	s_cmp_ge_i32 s62, s51
	s_mov_b32 s24, s62
	s_cbranch_scc0 .LBB0_1091

; #define PG8_STAGE(bufoff, gbase, voff) do { _Pragma("unroll") for (int _i = 0; _i < 2; ++_i) \
;         __builtin_amdgcn_global_load_lds((const unsigned*)((const char*)(gbase) + (voff)[_i]), (PG8_LAS unsigned*)(lds + (bufoff) + ldsw + _i * 8192), 16, 0, 0); } while (0)
; #define PG8_LDA(dst, b, h) do { _Pragma("unroll") for (int m = 0; m < 4; ++m) _Pragma("unroll") for (int k = 0; k < 2; ++k) dst[m][k] = *(const PG8_LAS bf16x8*)(lds + PG8_SA(b, h) + aoff + m * 2048 + k * 1024); } while (0)
; #define PG8_MMA(ai, bj, At, Bt) do { __builtin_amdgcn_s_setprio(1); _Pragma("unroll") for (int m = 0; m < 4; ++m) _Pragma("unroll") for (int n = 0; n < 2; ++n) _Pragma("unroll") for (int k = 0; k < 2; ++k) \
;         acc[ai][bj][m][n] = __builtin_amdgcn_mfma_f32_16x16x32_bf16(Bt[n][k], At[m][k], acc[ai][bj][m][n], 0, 0, 0); __builtin_amdgcn_s_setprio(0); } while (0)
; #define PG8_WAIT_L(n) asm volatile("s_waitcnt lgkmcnt(" #n ")" ::: "memory")
; #define PG8_WAIT_V8_UNLESS(flag) asm volatile("s_cmp_lg_i32 %0, 0\n\ts_cbranch_scc1 .Lpg8rx%=\n\ts_waitcnt vmcnt(8)\n.Lpg8rx%=:" :: "s"(__builtin_amdgcn_readfirstlane(flag)) : "scc", "memory")
; #define PG8_BAR __builtin_amdgcn_s_barrier()
; #define PG8_SCHED __builtin_amdgcn_sched_barrier(0)
; template <class Epi, class Sched, bool ALIGN_EPI = false, bool SP2 = false>
; __device__ __forceinline__ void gemm_phase(PG8_LAS unsigned char* lds, const Gemm g, const Sched& S, const Epi& E) {
;     ...
;             PG8_WAIT_V8_UNLESS(rx); PG8_WAIT_L(0); PG8_BAR; PG8_MMA(0, 0, At, B0); PG8_MMA(0, 1, At, B1); PG8_BAR; PG8_SCHED;
;             PG8_STAGE(PG8_SB(0, 0), b2, voffB); PG8_STAGE(PG8_SB(0, 1), b2 + hstep, voffB); PG8_STAGE(PG8_SA(0, 0), a2, voffA); PG8_SCHED; PG8_LDA(At, 0, 1);
;             PG8_WAIT_V8_UNLESS(rx); PG8_WAIT_L(0); PG8_BAR; PG8_MMA(1, 0, At, B0); PG8_MMA(1, 1, At, B1); PG8_BAR; PG8_SCHED;
.Lpg8rx10:
	s_waitcnt lgkmcnt(0)
	s_setprio 2
	s_barrier
	v_mfma_f32_16x16x32_bf16 v[124:127], v[132:135], v[180:183], v[124:127]
	v_mfma_f32_16x16x32_bf16 v[120:123], v[140:143], v[180:183], v[120:123]
	v_mfma_f32_16x16x32_bf16 v[108:111], v[132:135], v[188:191], v[108:111]
	v_mfma_f32_16x16x32_bf16 v[104:107], v[140:143], v[188:191], v[104:107]
	v_mfma_f32_16x16x32_bf16 v[92:95], v[132:135], v[208:211], v[92:95]
	v_mfma_f32_16x16x32_bf16 v[88:91], v[140:143], v[208:211], v[88:91]
	v_mfma_f32_16x16x32_bf16 v[76:79], v[132:135], v[216:219], v[76:79]
	v_mfma_f32_16x16x32_bf16 v[72:75], v[140:143], v[216:219], v[72:75]
	v_mfma_f32_16x16x32_bf16 v[124:127], v[136:139], v[184:187], v[124:127]
	v_mfma_f32_16x16x32_bf16 v[120:123], v[144:147], v[184:187], v[120:123]
	v_mfma_f32_16x16x32_bf16 v[108:111], v[136:139], v[204:207], v[108:111]
	v_mfma_f32_16x16x32_bf16 v[104:107], v[144:147], v[204:207], v[104:107]
	v_mfma_f32_16x16x32_bf16 v[92:95], v[136:139], v[212:215], v[92:95]
	v_mfma_f32_16x16x32_bf16 v[88:91], v[144:147], v[212:215], v[88:91]
	v_mfma_f32_16x16x32_bf16 v[76:79], v[136:139], v[220:223], v[76:79]
	v_mfma_f32_16x16x32_bf16 v[72:75], v[144:147], v[220:223], v[72:75]
	v_mfma_f32_16x16x32_bf16 v[116:119], v[160:163], v[180:183], v[116:119]
	v_mfma_f32_16x16x32_bf16 v[112:115], v[168:171], v[180:183], v[112:115]
	v_mfma_f32_16x16x32_bf16 v[100:103], v[160:163], v[188:191], v[100:103]
	v_mfma_f32_16x16x32_bf16 v[96:99], v[168:171], v[188:191], v[96:99]
	v_mfma_f32_16x16x32_bf16 v[84:87], v[160:163], v[208:211], v[84:87]
	v_mfma_f32_16x16x32_bf16 v[80:83], v[168:171], v[208:211], v[80:83]
	v_mfma_f32_16x16x32_bf16 v[68:71], v[160:163], v[216:219], v[68:71]
	v_mfma_f32_16x16x32_bf16 v[64:67], v[168:171], v[216:219], v[64:67]
	v_mfma_f32_16x16x32_bf16 v[116:119], v[164:167], v[184:187], v[116:119]
	v_mfma_f32_16x16x32_bf16 v[112:115], v[176:179], v[184:187], v[112:115]
	v_mfma_f32_16x16x32_bf16 v[100:103], v[164:167], v[204:207], v[100:103]
	v_mfma_f32_16x16x32_bf16 v[96:99], v[176:179], v[204:207], v[96:99]
	v_mfma_f32_16x16x32_bf16 v[84:87], v[164:167], v[212:215], v[84:87]
	v_mfma_f32_16x16x32_bf16 v[80:83], v[176:179], v[212:215], v[80:83]
	s_setprio 3
	s_barrier
	v_mfma_f32_16x16x32_bf16 v[68:71], v[164:167], v[220:223], v[68:71]
	v_mfma_f32_16x16x32_bf16 v[64:67], v[176:179], v[220:223], v[64:67]
	s_setprio 0
	ds_read_b128 v[180:183], v175 offset:16384
	ds_read_b128 v[184:187], v175 offset:17408
	ds_read_b128 v[188:191], v175 offset:18432
	ds_read_b128 v[204:207], v175 offset:19456
	ds_read_b128 v[208:211], v175 offset:20480
	ds_read_b128 v[212:215], v175 offset:21504
	ds_read_b128 v[216:219], v175 offset:22528
	ds_read_b128 v[220:223], v175 offset:23552
	s_add_u32 s60, s28, 0x40000
	s_addc_u32 s61, s29, 0
	s_add_i32 m0, s65, s35
	s_nop 0
	global_load_lds_dwordx4 v150, s[28:29]
	s_add_i32 m0, m0, 0x2000
	s_nop 0
	global_load_lds_dwordx4 v154, s[28:29]
	s_add_i32 m0, s66, s35
	s_nop 0
	global_load_lds_dwordx4 v150, s[60:61]
	s_add_i32 m0, m0, 0x2000
	s_nop 0
	global_load_lds_dwordx4 v154, s[60:61]
	s_mov_b32 m0, s41
	s_nop 0
	global_load_lds_dwordx4 v148, s[30:31]
	s_mov_b32 m0, s48
	s_nop 0
	global_load_lds_dwordx4 v152, s[30:31]
	s_cmp_lg_i32 s67, 0
	s_cbranch_scc1 .Lpg8rx11
	s_waitcnt vmcnt(8)
.Lpg8rx11:
	s_waitcnt lgkmcnt(0)
	s_setprio 2
	s_barrier
	v_mfma_f32_16x16x32_bf16 v[60:63], v[132:135], v[180:183], v[60:63]
	v_mfma_f32_16x16x32_bf16 v[56:59], v[140:143], v[180:183], v[56:59]
	v_mfma_f32_16x16x32_bf16 v[44:47], v[132:135], v[188:191], v[44:47]
	v_mfma_f32_16x16x32_bf16 v[40:43], v[140:143], v[188:191], v[40:43]
	v_mfma_f32_16x16x32_bf16 v[28:31], v[132:135], v[208:211], v[28:31]
	v_mfma_f32_16x16x32_bf16 v[24:27], v[140:143], v[208:211], v[24:27]
	v_mfma_f32_16x16x32_bf16 v[12:15], v[132:135], v[216:219], v[12:15]
	v_mfma_f32_16x16x32_bf16 v[8:11], v[140:143], v[216:219], v[8:11]
	v_mfma_f32_16x16x32_bf16 v[60:63], v[136:139], v[184:187], v[60:63]
	v_mfma_f32_16x16x32_bf16 v[56:59], v[144:147], v[184:187], v[56:59]
	v_mfma_f32_16x16x32_bf16 v[44:47], v[136:139], v[204:207], v[44:47]
	v_mfma_f32_16x16x32_bf16 v[40:43], v[144:147], v[204:207], v[40:43]
	v_mfma_f32_16x16x32_bf16 v[28:31], v[136:139], v[212:215], v[28:31]
	v_mfma_f32_16x16x32_bf16 v[24:27], v[144:147], v[212:215], v[24:27]
	v_mfma_f32_16x16x32_bf16 v[12:15], v[136:139], v[220:223], v[12:15]
	v_mfma_f32_16x16x32_bf16 v[8:11], v[144:147], v[220:223], v[8:11]
	v_mfma_f32_16x16x32_bf16 v[52:55], v[160:163], v[180:183], v[52:55]
	v_mfma_f32_16x16x32_bf16 v[48:51], v[168:171], v[180:183], v[48:51]
	v_mfma_f32_16x16x32_bf16 v[36:39], v[160:163], v[188:191], v[36:39]
	v_mfma_f32_16x16x32_bf16 v[32:35], v[168:171], v[188:191], v[32:35]
	v_mfma_f32_16x16x32_bf16 v[20:23], v[160:163], v[208:211], v[20:23]
	v_mfma_f32_16x16x32_bf16 v[16:19], v[168:171], v[208:211], v[16:19]
	v_mfma_f32_16x16x32_bf16 v[4:7], v[160:163], v[216:219], v[4:7]
	v_mfma_f32_16x16x32_bf16 v[0:3], v[168:171], v[216:219], v[0:3]
	v_mfma_f32_16x16x32_bf16 v[52:55], v[164:167], v[184:187], v[52:55]
	v_mfma_f32_16x16x32_bf16 v[48:51], v[176:179], v[184:187], v[48:51]
	v_mfma_f32_16x16x32_bf16 v[36:39], v[164:167], v[204:207], v[36:39]
	v_mfma_f32_16x16x32_bf16 v[32:35], v[176:179], v[204:207], v[32:35]
	v_mfma_f32_16x16x32_bf16 v[20:23], v[164:167], v[212:215], v[20:23]
	v_mfma_f32_16x16x32_bf16 v[16:19], v[176:179], v[212:215], v[16:19]
	s_setprio 3
	s_barrier
; #define PG8_STAGE(bufoff, gbase, voff) do { _Pragma("unroll") for (int _i = 0; _i < 2; ++_i) \
;         __builtin_amdgcn_global_load_lds((const unsigned*)((const char*)(gbase) + (voff)[_i]), (PG8_LAS unsigned*)(lds + (bufoff) + ldsw + _i * 8192), 16, 0, 0); } while (0)
; #define PG8_LDA(dst, b, h) do { _Pragma("unroll") for (int m = 0; m < 4; ++m) _Pragma("unroll") for (int k = 0; k < 2; ++k) dst[m][k] = *(const PG8_LAS bf16x8*)(lds + PG8_SA(b, h) + aoff + m * 2048 + k * 1024); } while (0)
; #define PG8_LDB(dst, b, h) do { _Pragma("unroll") for (int n = 0; n < 2; ++n) _Pragma("unroll") for (int k = 0; k < 2; ++k) dst[n][k] = *(const PG8_LAS bf16x8*)(lds + PG8_SB(b, h) + boff + n * 2048 + k * 1024); } while (0)
; #define PG8_MMA(ai, bj, At, Bt) do { __builtin_amdgcn_s_setprio(1); _Pragma("unroll") for (int m = 0; m < 4; ++m) _Pragma("unroll") for (int n = 0; n < 2; ++n) _Pragma("unroll") for (int k = 0; k < 2; ++k) \
;         acc[ai][bj][m][n] = __builtin_amdgcn_mfma_f32_16x16x32_bf16(Bt[n][k], At[m][k], acc[ai][bj][m][n], 0, 0, 0); __builtin_amdgcn_s_setprio(0); } while (0)
; #define PG8_WAIT_V(n) asm volatile("s_waitcnt vmcnt(" #n ")" ::: "memory")
; #define PG8_WAIT_L(n) asm volatile("s_waitcnt lgkmcnt(" #n ")" ::: "memory")
; #define PG8_WAIT_V8_UNLESS(flag) asm volatile("s_cmp_lg_i32 %0, 0\n\ts_cbranch_scc1 .Lpg8rx%=\n\ts_waitcnt vmcnt(8)\n.Lpg8rx%=:" :: "s"(__builtin_amdgcn_readfirstlane(flag)) : "scc", "memory")
; #define PG8_BAR __builtin_amdgcn_s_barrier()
; template <class Epi, class Sched, bool ALIGN_EPI = false, bool SP2 = false>
; __device__ __forceinline__ void gemm_phase(PG8_LAS unsigned char* lds, const Gemm g, const Sched& S, const Epi& E) {
;     ...
;             PG8_WAIT_V8_UNLESS(rx); PG8_WAIT_L(0); PG8_BAR; PG8_MMA(1, 0, At, B0); PG8_MMA(1, 1, At, B1); PG8_BAR; PG8_SCHED;
;             PG8_STAGE(PG8_SA(0, 1), a2 + hstep, voffA); PG8_SCHED; PG8_LDB(B0, 1, 0); PG8_LDB(B1, 1, 1); PG8_SCHED; PG8_LDA(At, 1, 0);
;             PG8_WAIT_V(8); PG8_WAIT_L(0); PG8_BAR; PG8_MMA(0, 0, At, B0); PG8_MMA(0, 1, At, B1); PG8_BAR; PG8_SCHED;
;             PG8_STAGE(PG8_SB(1, 0), b3, voffB); PG8_STAGE(PG8_SB(1, 1), b3 + hstep, voffB); PG8_STAGE(PG8_SA(1, 0), a3, voffA); PG8_SCHED; PG8_LDA(At, 1, 1);
;             PG8_WAIT_V(8); PG8_WAIT_L(0); PG8_BAR; PG8_MMA(1, 0, At, B0); PG8_MMA(1, 1, At, B1); PG8_BAR; PG8_SCHED;
	v_mfma_f32_16x16x32_bf16 v[4:7], v[164:167], v[220:223], v[4:7]
	v_mfma_f32_16x16x32_bf16 v[0:3], v[176:179], v[220:223], v[0:3]
	s_setprio 0
	s_mov_b64 s[98:99], s[30:31]
	s_add_u32 s100, s30, 0x40000
	s_addc_u32 s101, s31, 0
	s_add_i32 s30, 0, 0x18000
	s_add_i32 s31, 0, 0x1c000
	v_add_u32_e32 v144, s30, v174
	v_add_u32_e32 v176, s31, v174
	ds_read_b128 v[132:135], v144
	ds_read_b128 v[136:139], v144 offset:1024
	ds_read_b128 v[140:143], v144 offset:2048
	ds_read_b128 v[144:147], v144 offset:3072
	ds_read_b128 v[160:163], v176
	ds_read_b128 v[164:167], v176 offset:1024
	ds_read_b128 v[168:171], v176 offset:2048
	ds_read_b128 v[176:179], v176 offset:3072
	ds_read_b128 v[180:183], v175 offset:32768
	ds_read_b128 v[184:187], v175 offset:33792
	ds_read_b128 v[188:191], v175 offset:34816
	ds_read_b128 v[204:207], v175 offset:35840
	ds_read_b128 v[208:211], v175 offset:36864
	ds_read_b128 v[212:215], v175 offset:37888
	ds_read_b128 v[216:219], v175 offset:38912
	ds_read_b128 v[220:223], v175 offset:39936
	s_mov_b32 m0, s50
	s_nop 0
	global_load_lds_dwordx4 v148, s[100:101]
	s_mov_b32 m0, s51
	s_nop 0
	global_load_lds_dwordx4 v152, s[100:101]
	s_waitcnt vmcnt(8)
	s_waitcnt lgkmcnt(0)
	s_setprio 2
	s_barrier
	v_mfma_f32_16x16x32_bf16 v[124:127], v[132:135], v[180:183], v[124:127]
	v_mfma_f32_16x16x32_bf16 v[120:123], v[140:143], v[180:183], v[120:123]
	v_mfma_f32_16x16x32_bf16 v[108:111], v[132:135], v[188:191], v[108:111]
	v_mfma_f32_16x16x32_bf16 v[104:107], v[140:143], v[188:191], v[104:107]
	v_mfma_f32_16x16x32_bf16 v[92:95], v[132:135], v[208:211], v[92:95]
	v_mfma_f32_16x16x32_bf16 v[88:91], v[140:143], v[208:211], v[88:91]
	v_mfma_f32_16x16x32_bf16 v[76:79], v[132:135], v[216:219], v[76:79]
	v_mfma_f32_16x16x32_bf16 v[72:75], v[140:143], v[216:219], v[72:75]
	v_mfma_f32_16x16x32_bf16 v[124:127], v[136:139], v[184:187], v[124:127]
	v_mfma_f32_16x16x32_bf16 v[120:123], v[144:147], v[184:187], v[120:123]
	v_mfma_f32_16x16x32_bf16 v[108:111], v[136:139], v[204:207], v[108:111]
	v_mfma_f32_16x16x32_bf16 v[104:107], v[144:147], v[204:207], v[104:107]
	v_mfma_f32_16x16x32_bf16 v[92:95], v[136:139], v[212:215], v[92:95]
	v_mfma_f32_16x16x32_bf16 v[88:91], v[144:147], v[212:215], v[88:91]
	v_mfma_f32_16x16x32_bf16 v[76:79], v[136:139], v[220:223], v[76:79]
	v_mfma_f32_16x16x32_bf16 v[72:75], v[144:147], v[220:223], v[72:75]
	v_mfma_f32_16x16x32_bf16 v[116:119], v[160:163], v[180:183], v[116:119]
	v_mfma_f32_16x16x32_bf16 v[112:115], v[168:171], v[180:183], v[112:115]
	v_mfma_f32_16x16x32_bf16 v[100:103], v[160:163], v[188:191], v[100:103]
	v_mfma_f32_16x16x32_bf16 v[96:99], v[168:171], v[188:191], v[96:99]
	v_mfma_f32_16x16x32_bf16 v[84:87], v[160:163], v[208:211], v[84:87]
	v_mfma_f32_16x16x32_bf16 v[80:83], v[168:171], v[208:211], v[80:83]
	v_mfma_f32_16x16x32_bf16 v[68:71], v[160:163], v[216:219], v[68:71]
	v_mfma_f32_16x16x32_bf16 v[64:67], v[168:171], v[216:219], v[64:67]
	v_mfma_f32_16x16x32_bf16 v[116:119], v[164:167], v[184:187], v[116:119]
	v_mfma_f32_16x16x32_bf16 v[112:115], v[176:179], v[184:187], v[112:115]
	v_mfma_f32_16x16x32_bf16 v[100:103], v[164:167], v[204:207], v[100:103]
	v_mfma_f32_16x16x32_bf16 v[96:99], v[176:179], v[204:207], v[96:99]
	v_mfma_f32_16x16x32_bf16 v[84:87], v[164:167], v[212:215], v[84:87]
	v_mfma_f32_16x16x32_bf16 v[80:83], v[176:179], v[212:215], v[80:83]
	s_setprio 3
	s_barrier
	v_mfma_f32_16x16x32_bf16 v[68:71], v[164:167], v[220:223], v[68:71]
	v_mfma_f32_16x16x32_bf16 v[64:67], v[176:179], v[220:223], v[64:67]
	s_setprio 0
	ds_read_b128 v[180:183], v175 offset:49152
	ds_read_b128 v[184:187], v175 offset:50176
	ds_read_b128 v[188:191], v175 offset:51200
	ds_read_b128 v[204:207], v175 offset:52224
	ds_read_b128 v[208:211], v175 offset:53248
	ds_read_b128 v[212:215], v175 offset:54272
	ds_read_b128 v[216:219], v175 offset:55296
	ds_read_b128 v[220:223], v175 offset:56320
	s_add_u32 s100, s28, 0x80
	s_addc_u32 s101, s29, 0
	s_add_u32 s28, s28, 0x40080
	s_addc_u32 s29, s29, 0
	s_add_u32 s98, s98, 0x80
	s_addc_u32 s99, s99, 0
	s_add_i32 m0, s30, s35
	s_nop 0
	global_load_lds_dwordx4 v150, s[100:101]
	s_add_i32 m0, m0, 0x2000
	s_nop 0
	global_load_lds_dwordx4 v154, s[100:101]
	s_add_i32 m0, s31, s35
	s_nop 0
	global_load_lds_dwordx4 v150, s[28:29]
	s_add_i32 m0, m0, 0x2000
	s_nop 0
	global_load_lds_dwordx4 v154, s[28:29]
	s_mov_b32 m0, s52
	s_nop 0
	global_load_lds_dwordx4 v148, s[98:99]
	s_mov_b32 m0, s53
	s_nop 0
	global_load_lds_dwordx4 v152, s[98:99]
	s_waitcnt vmcnt(8)
	s_waitcnt lgkmcnt(0)
	s_setprio 2
	s_barrier
	v_mfma_f32_16x16x32_bf16 v[60:63], v[132:135], v[180:183], v[60:63]
	v_mfma_f32_16x16x32_bf16 v[56:59], v[140:143], v[180:183], v[56:59]
	v_mfma_f32_16x16x32_bf16 v[44:47], v[132:135], v[188:191], v[44:47]
	v_mfma_f32_16x16x32_bf16 v[40:43], v[140:143], v[188:191], v[40:43]
	v_mfma_f32_16x16x32_bf16 v[28:31], v[132:135], v[208:211], v[28:31]
	v_mfma_f32_16x16x32_bf16 v[24:27], v[140:143], v[208:211], v[24:27]
	v_mfma_f32_16x16x32_bf16 v[12:15], v[132:135], v[216:219], v[12:15]
	v_mfma_f32_16x16x32_bf16 v[8:11], v[140:143], v[216:219], v[8:11]
	v_mfma_f32_16x16x32_bf16 v[60:63], v[136:139], v[184:187], v[60:63]
	v_mfma_f32_16x16x32_bf16 v[56:59], v[144:147], v[184:187], v[56:59]
	v_mfma_f32_16x16x32_bf16 v[44:47], v[136:139], v[204:207], v[44:47]
	v_mfma_f32_16x16x32_bf16 v[40:43], v[144:147], v[204:207], v[40:43]
	v_mfma_f32_16x16x32_bf16 v[28:31], v[136:139], v[212:215], v[28:31]
	v_mfma_f32_16x16x32_bf16 v[24:27], v[144:147], v[212:215], v[24:27]
	v_mfma_f32_16x16x32_bf16 v[12:15], v[136:139], v[220:223], v[12:15]
	v_mfma_f32_16x16x32_bf16 v[8:11], v[144:147], v[220:223], v[8:11]
	v_mfma_f32_16x16x32_bf16 v[52:55], v[160:163], v[180:183], v[52:55]
	v_mfma_f32_16x16x32_bf16 v[48:51], v[168:171], v[180:183], v[48:51]
	v_mfma_f32_16x16x32_bf16 v[36:39], v[160:163], v[188:191], v[36:39]
	v_mfma_f32_16x16x32_bf16 v[32:35], v[168:171], v[188:191], v[32:35]
	v_mfma_f32_16x16x32_bf16 v[20:23], v[160:163], v[208:211], v[20:23]
	v_mfma_f32_16x16x32_bf16 v[16:19], v[168:171], v[208:211], v[16:19]
	v_mfma_f32_16x16x32_bf16 v[4:7], v[160:163], v[216:219], v[4:7]
	v_mfma_f32_16x16x32_bf16 v[0:3], v[168:171], v[216:219], v[0:3]
	v_mfma_f32_16x16x32_bf16 v[52:55], v[164:167], v[184:187], v[52:55]
	v_mfma_f32_16x16x32_bf16 v[48:51], v[176:179], v[184:187], v[48:51]
	v_mfma_f32_16x16x32_bf16 v[36:39], v[164:167], v[204:207], v[36:39]
	v_mfma_f32_16x16x32_bf16 v[32:35], v[176:179], v[204:207], v[32:35]
	v_mfma_f32_16x16x32_bf16 v[20:23], v[164:167], v[212:215], v[20:23]
	v_mfma_f32_16x16x32_bf16 v[16:19], v[176:179], v[212:215], v[16:19]
	s_setprio 3
	s_barrier
	v_mfma_f32_16x16x32_bf16 v[4:7], v[164:167], v[220:223], v[4:7]
	v_mfma_f32_16x16x32_bf16 v[0:3], v[176:179], v[220:223], v[0:3]
	s_setprio 0
	s_add_i32 s59, s59, 2
	s_add_u32 vcc_lo, vcc_lo, 0x100
	s_addc_u32 vcc_hi, vcc_hi, 0
	s_cmp_gt_u32 s59, 13
	s_cbranch_scc0 .LBB0_1133
	s_and_b64 vcc, exec, s[14:15]
	s_cbranch_vccz .LBB0_1136
	s_barrier
